# K-loop trim + closing setprio 0 moved behind the closing barrier
# baseline (speedup 1.0000x reference)
; #define PG8_STAGE(bufoff, gbase, voff) do { _Pragma("unroll") for (int _i = 0; _i < 2; ++_i) \
;         __builtin_amdgcn_global_load_lds((const unsigned*)((const char*)(gbase) + (voff)[_i]), (LAS unsigned*)(lds + (bufoff) + ldsw + _i * 8192), 16, 0, 0); } while (0)
; #define PG8_LDA(dst, b, h) do { _Pragma("unroll") for (int m = 0; m < 4; ++m) _Pragma("unroll") for (int k = 0; k < 2; ++k) dst[m][k] = *(const LAS bf16x8*)(lds + PG8_SA(b, h) + aoff + m * 2048 + k * 1024); } while (0)
; #define PG8_LDB(dst, b, h) do { _Pragma("unroll") for (int n = 0; n < 2; ++n) _Pragma("unroll") for (int k = 0; k < 2; ++k) dst[n][k] = *(const LAS bf16x8*)(lds + PG8_SB(b, h) + boff + n * 2048 + k * 1024); } while (0)
; #define PG8_MMA(ai, bj, At, Bt) do { __builtin_amdgcn_s_setprio(1); _Pragma("unroll") for (int m = 0; m < 4; ++m) _Pragma("unroll") for (int n = 0; n < 2; ++n) _Pragma("unroll") for (int k = 0; k < 2; ++k) \
;         acc[ai][bj][m][n] = __builtin_amdgcn_mfma_f32_16x16x32_bf16(Bt[n][k], At[m][k], acc[ai][bj][m][n], 0, 0, 0); __builtin_amdgcn_s_setprio(0); } while (0)
; #define PG8_BAR __builtin_amdgcn_s_barrier()
; template <class Epi, int AMODE>
; __device__ __forceinline__ void gemm_phase(LAS unsigned char* lds, const Gemm g, const StaticOrder& S, const Epi& E, int stagger_us, int tid_in) {
;     ...
;         const bool has_next = S.next(ui + 1, nxt);
;         const char* nA = has_next ? Abase + (size_t)nxt.pm * tstepA : cA; const char* nB = has_next ? (const char*)g.Bt + (size_t)nxt.pn * tstepB : cB;
;         for (int t = 0; t < nt; t += 2) {
;             const bool last = (t == nt - 2);
;             const char* a1 = cA + (size_t)(t + 1) * kstep;
;             const char* a2 = last ? nA : cA + (size_t)(t + 2) * kstep; const char* b2 = last ? nB : cB + (size_t)(t + 2) * kstep;
;             const char* a3 = a2 + kstep; const char* b3 = b2 + kstep;
;             PG8_LDB(B0, 0, 0); PG8_LDB(B1, 0, 1); PG8_SCHED; PG8_LDA(At, 0, 0); PG8_STAGE(PG8_SA(1, 1), a1 + hstepA, voffA);
;             PG8_WAIT_V(8); PG8_WAIT_L(0); PG8_BAR; PG8_MMA(0, 0, At, B0); PG8_MMA(0, 1, At, B1); PG8_BAR; PG8_SCHED;
;             PG8_LDA(At, 0, 1); PG8_STAGE(PG8_SB(0, 0), b2, voffB); PG8_STAGE(PG8_SB(0, 1), b2 + hstepB, voffB); PG8_STAGE(PG8_SA(0, 0), a2, voffA);
;             PG8_WAIT_V(8); PG8_WAIT_L(0); PG8_BAR; PG8_MMA(1, 0, At, B0); PG8_MMA(1, 1, At, B1); PG8_BAR; PG8_SCHED;
.LBB0_396:
	s_add_u32 s4, s60, 0xfff80080
	s_addc_u32 s5, s61, -1
	s_add_i32 s30, 0, 0x10000
	s_cmp_eq_u32 s29, 28
	s_cselect_b32 s7, s27, s5
	s_cselect_b32 s6, s28, s4
	v_add_u32_e32 v140, s30, v162
	s_cselect_b32 s5, s49, vcc_hi
	s_cselect_b32 s4, s51, vcc_lo
	s_add_i32 s44, 0, 0x14000
	ds_read_b128 v[144:147], v140
	ds_read_b128 v[148:151], v140 offset:1024
	ds_read_b128 v[152:155], v140 offset:2048
	ds_read_b128 v[156:159], v140 offset:3072
	v_add_u32_e32 v140, s44, v162
	ds_read_b128 v[166:169], v140
	ds_read_b128 v[170:173], v140 offset:1024
	ds_read_b128 v[174:177], v140 offset:2048
	ds_read_b128 v[178:181], v140 offset:3072
	v_lshl_add_u64 v[140:141], s[60:61], 0, v[136:137]
	s_add_i32 m0, s57, 0xc000
	ds_read_b128 v[182:185], v164
	ds_read_b128 v[186:189], v164 offset:1024
	ds_read_b128 v[190:193], v164 offset:2048
	ds_read_b128 v[194:197], v164 offset:3072
	ds_read_b128 v[198:201], v164 offset:4096
	ds_read_b128 v[202:205], v164 offset:5120
	ds_read_b128 v[206:209], v164 offset:6144
	ds_read_b128 v[210:213], v164 offset:7168
	global_load_lds_dwordx4 v[140:141], off
	v_lshl_add_u64 v[140:141], s[60:61], 0, v[138:139]
	s_add_i32 m0, s57, 0xe000
	s_nop 0
	global_load_lds_dwordx4 v[140:141], off
	s_waitcnt vmcnt(8)
	s_waitcnt lgkmcnt(0)
	s_setprio 1
	s_barrier
	v_mfma_f32_16x16x32_bf16 v[126:129], v[144:147], v[182:185], v[126:129]
	v_mfma_f32_16x16x32_bf16 v[122:125], v[152:155], v[182:185], v[122:125]
	v_mfma_f32_16x16x32_bf16 v[110:113], v[144:147], v[190:193], v[110:113]
	v_mfma_f32_16x16x32_bf16 v[106:109], v[152:155], v[190:193], v[106:109]
	v_mfma_f32_16x16x32_bf16 v[94:97], v[144:147], v[198:201], v[94:97]
	v_mfma_f32_16x16x32_bf16 v[90:93], v[152:155], v[198:201], v[90:93]
	v_mfma_f32_16x16x32_bf16 v[78:81], v[144:147], v[206:209], v[78:81]
	v_mfma_f32_16x16x32_bf16 v[74:77], v[152:155], v[206:209], v[74:77]
	v_mfma_f32_16x16x32_bf16 v[126:129], v[148:151], v[186:189], v[126:129]
	v_mfma_f32_16x16x32_bf16 v[122:125], v[156:159], v[186:189], v[122:125]
	v_mfma_f32_16x16x32_bf16 v[110:113], v[148:151], v[194:197], v[110:113]
	v_mfma_f32_16x16x32_bf16 v[106:109], v[156:159], v[194:197], v[106:109]
	v_mfma_f32_16x16x32_bf16 v[94:97], v[148:151], v[202:205], v[94:97]
	v_mfma_f32_16x16x32_bf16 v[90:93], v[156:159], v[202:205], v[90:93]
	v_mfma_f32_16x16x32_bf16 v[78:81], v[148:151], v[210:213], v[78:81]
	v_mfma_f32_16x16x32_bf16 v[74:77], v[156:159], v[210:213], v[74:77]
	v_mfma_f32_16x16x32_bf16 v[118:121], v[166:169], v[182:185], v[118:121]
	v_mfma_f32_16x16x32_bf16 v[114:117], v[174:177], v[182:185], v[114:117]
	v_mfma_f32_16x16x32_bf16 v[102:105], v[166:169], v[190:193], v[102:105]
	v_mfma_f32_16x16x32_bf16 v[98:101], v[174:177], v[190:193], v[98:101]
	v_mfma_f32_16x16x32_bf16 v[86:89], v[166:169], v[198:201], v[86:89]
	v_mfma_f32_16x16x32_bf16 v[82:85], v[174:177], v[198:201], v[82:85]
	v_mfma_f32_16x16x32_bf16 v[70:73], v[166:169], v[206:209], v[70:73]
	v_mfma_f32_16x16x32_bf16 v[66:69], v[174:177], v[206:209], v[66:69]
	v_mfma_f32_16x16x32_bf16 v[118:121], v[170:173], v[186:189], v[118:121]
	v_mfma_f32_16x16x32_bf16 v[114:117], v[178:181], v[186:189], v[114:117]
	v_mfma_f32_16x16x32_bf16 v[102:105], v[170:173], v[194:197], v[102:105]
	v_mfma_f32_16x16x32_bf16 v[98:101], v[178:181], v[194:197], v[98:101]
	v_mfma_f32_16x16x32_bf16 v[86:89], v[170:173], v[202:205], v[86:89]
	v_mfma_f32_16x16x32_bf16 v[82:85], v[178:181], v[202:205], v[82:85]
	v_mfma_f32_16x16x32_bf16 v[70:73], v[170:173], v[210:213], v[70:73]
	v_mfma_f32_16x16x32_bf16 v[66:69], v[178:181], v[210:213], v[66:69]
	s_barrier
	s_setprio 0
	s_add_i32 s30, s30, s66
	v_lshl_add_u64 v[140:141], s[4:5], 0, v[0:1]
	s_mov_b32 m0, s30
	ds_read_b128 v[182:185], v164 offset:16384
	ds_read_b128 v[186:189], v164 offset:17408
	ds_read_b128 v[190:193], v164 offset:18432
	ds_read_b128 v[194:197], v164 offset:19456
	ds_read_b128 v[198:201], v164 offset:20480
	ds_read_b128 v[202:205], v164 offset:21504
	ds_read_b128 v[206:209], v164 offset:22528
	ds_read_b128 v[210:213], v164 offset:23552
	global_load_lds_dwordx4 v[140:141], off
	s_add_i32 m0, s30, 0x2000
	s_add_u32 s30, s4, 0x80000
	v_lshl_add_u64 v[160:161], s[4:5], 0, v[130:131]
	s_addc_u32 s31, s5, 0
	s_add_i32 s44, s44, s66
	global_load_lds_dwordx4 v[160:161], off
	v_lshl_add_u64 v[214:215], s[30:31], 0, v[0:1]
	s_mov_b32 m0, s44
	v_lshl_add_u64 v[216:217], s[6:7], 0, v[132:133]
	global_load_lds_dwordx4 v[214:215], off
	v_lshl_add_u64 v[214:215], s[30:31], 0, v[130:131]
	s_add_i32 m0, s44, 0x2000
	s_nop 0
	global_load_lds_dwordx4 v[214:215], off
	v_lshl_add_u64 v[214:215], s[6:7], 0, v[134:135]
	s_mov_b32 m0, s57
	s_nop 0
	global_load_lds_dwordx4 v[214:215], off
	s_mov_b32 m0, s59
	s_nop 0
	global_load_lds_dwordx4 v[216:217], off
	s_waitcnt vmcnt(8)
	s_waitcnt lgkmcnt(0)
	s_setprio 1
	s_barrier
; #define PG8_STAGE(bufoff, gbase, voff) do { _Pragma("unroll") for (int _i = 0; _i < 2; ++_i) \
;         __builtin_amdgcn_global_load_lds((const unsigned*)((const char*)(gbase) + (voff)[_i]), (LAS unsigned*)(lds + (bufoff) + ldsw + _i * 8192), 16, 0, 0); } while (0)
; #define PG8_LDA(dst, b, h) do { _Pragma("unroll") for (int m = 0; m < 4; ++m) _Pragma("unroll") for (int k = 0; k < 2; ++k) dst[m][k] = *(const LAS bf16x8*)(lds + PG8_SA(b, h) + aoff + m * 2048 + k * 1024); } while (0)
; #define PG8_LDB(dst, b, h) do { _Pragma("unroll") for (int n = 0; n < 2; ++n) _Pragma("unroll") for (int k = 0; k < 2; ++k) dst[n][k] = *(const LAS bf16x8*)(lds + PG8_SB(b, h) + boff + n * 2048 + k * 1024); } while (0)
; #define PG8_MMA(ai, bj, At, Bt) do { __builtin_amdgcn_s_setprio(1); _Pragma("unroll") for (int m = 0; m < 4; ++m) _Pragma("unroll") for (int n = 0; n < 2; ++n) _Pragma("unroll") for (int k = 0; k < 2; ++k) \
;         acc[ai][bj][m][n] = __builtin_amdgcn_mfma_f32_16x16x32_bf16(Bt[n][k], At[m][k], acc[ai][bj][m][n], 0, 0, 0); __builtin_amdgcn_s_setprio(0); } while (0)
; #define PG8_WAIT_V(n) asm volatile("s_waitcnt vmcnt(" #n ")" ::: "memory")
; #define PG8_WAIT_L(n) asm volatile("s_waitcnt lgkmcnt(" #n ")" ::: "memory")
; #define PG8_BAR __builtin_amdgcn_s_barrier()
; #define PG8_SCHED __builtin_amdgcn_sched_barrier(0)
; template <class Epi, int AMODE>
; __device__ __forceinline__ void gemm_phase(LAS unsigned char* lds, const Gemm g, const StaticOrder& S, const Epi& E, int stagger_us, int tid_in) {
;     ...
;             PG8_WAIT_V(8); PG8_WAIT_L(0); PG8_BAR; PG8_MMA(1, 0, At, B0); PG8_MMA(1, 1, At, B1); PG8_BAR; PG8_SCHED;
;             PG8_LDB(B0, 1, 0); PG8_LDB(B1, 1, 1); PG8_SCHED; PG8_LDA(At, 1, 0); PG8_STAGE(PG8_SA(0, 1), a2 + hstepA, voffA);
;             PG8_WAIT_V(8); PG8_WAIT_L(0); PG8_BAR; PG8_MMA(0, 0, At, B0); PG8_MMA(0, 1, At, B1); PG8_BAR; PG8_SCHED;
	v_mfma_f32_16x16x32_bf16 v[62:65], v[144:147], v[182:185], v[62:65]
	v_mfma_f32_16x16x32_bf16 v[58:61], v[152:155], v[182:185], v[58:61]
	v_mfma_f32_16x16x32_bf16 v[46:49], v[144:147], v[190:193], v[46:49]
	v_mfma_f32_16x16x32_bf16 v[42:45], v[152:155], v[190:193], v[42:45]
	v_mfma_f32_16x16x32_bf16 v[30:33], v[144:147], v[198:201], v[30:33]
	v_mfma_f32_16x16x32_bf16 v[26:29], v[152:155], v[198:201], v[26:29]
	v_mfma_f32_16x16x32_bf16 v[14:17], v[144:147], v[206:209], v[14:17]
	v_mfma_f32_16x16x32_bf16 v[10:13], v[152:155], v[206:209], v[10:13]
	v_mfma_f32_16x16x32_bf16 v[62:65], v[148:151], v[186:189], v[62:65]
	v_mfma_f32_16x16x32_bf16 v[58:61], v[156:159], v[186:189], v[58:61]
	v_mfma_f32_16x16x32_bf16 v[46:49], v[148:151], v[194:197], v[46:49]
	v_mfma_f32_16x16x32_bf16 v[42:45], v[156:159], v[194:197], v[42:45]
	v_mfma_f32_16x16x32_bf16 v[30:33], v[148:151], v[202:205], v[30:33]
	v_mfma_f32_16x16x32_bf16 v[26:29], v[156:159], v[202:205], v[26:29]
	v_mfma_f32_16x16x32_bf16 v[14:17], v[148:151], v[210:213], v[14:17]
	v_mfma_f32_16x16x32_bf16 v[10:13], v[156:159], v[210:213], v[10:13]
	v_mfma_f32_16x16x32_bf16 v[54:57], v[166:169], v[182:185], v[54:57]
	v_mfma_f32_16x16x32_bf16 v[50:53], v[174:177], v[182:185], v[50:53]
	v_mfma_f32_16x16x32_bf16 v[38:41], v[166:169], v[190:193], v[38:41]
	v_mfma_f32_16x16x32_bf16 v[34:37], v[174:177], v[190:193], v[34:37]
	v_mfma_f32_16x16x32_bf16 v[22:25], v[166:169], v[198:201], v[22:25]
	v_mfma_f32_16x16x32_bf16 v[18:21], v[174:177], v[198:201], v[18:21]
	v_mfma_f32_16x16x32_bf16 v[6:9], v[166:169], v[206:209], v[6:9]
	v_mfma_f32_16x16x32_bf16 v[2:5], v[174:177], v[206:209], v[2:5]
	v_mfma_f32_16x16x32_bf16 v[54:57], v[170:173], v[186:189], v[54:57]
	v_mfma_f32_16x16x32_bf16 v[50:53], v[178:181], v[186:189], v[50:53]
	v_mfma_f32_16x16x32_bf16 v[38:41], v[170:173], v[194:197], v[38:41]
	v_mfma_f32_16x16x32_bf16 v[34:37], v[178:181], v[194:197], v[34:37]
	v_mfma_f32_16x16x32_bf16 v[22:25], v[170:173], v[202:205], v[22:25]
	v_mfma_f32_16x16x32_bf16 v[18:21], v[178:181], v[202:205], v[18:21]
	v_mfma_f32_16x16x32_bf16 v[6:9], v[170:173], v[210:213], v[6:9]
	v_mfma_f32_16x16x32_bf16 v[2:5], v[178:181], v[210:213], v[2:5]
	s_barrier
	s_setprio 0
	s_add_i32 s30, 0, 0x18000
	v_add_u32_e32 v142, s30, v162
	s_add_i32 s31, 0, 0x1c000
	ds_read_b128 v[144:147], v142
	ds_read_b128 v[148:151], v142 offset:1024
	ds_read_b128 v[152:155], v142 offset:2048
	ds_read_b128 v[156:159], v142 offset:3072
	v_add_u32_e32 v142, s31, v162
	ds_read_b128 v[166:169], v142
	ds_read_b128 v[170:173], v142 offset:1024
	ds_read_b128 v[174:177], v142 offset:2048
	ds_read_b128 v[178:181], v142 offset:3072
	s_add_u32 s6, s6, 0x80000
	s_addc_u32 s7, s7, 0
	s_mov_b32 m0, s87
	v_lshl_add_u64 v[218:219], s[6:7], 0, v[134:135]
	ds_read_b128 v[182:185], v164 offset:32768
	ds_read_b128 v[186:189], v164 offset:33792
	ds_read_b128 v[190:193], v164 offset:34816
	ds_read_b128 v[194:197], v164 offset:35840
	ds_read_b128 v[198:201], v164 offset:36864
	ds_read_b128 v[202:205], v164 offset:37888
	ds_read_b128 v[206:209], v164 offset:38912
	ds_read_b128 v[210:213], v164 offset:39936
	global_load_lds_dwordx4 v[218:219], off
	v_lshl_add_u64 v[218:219], s[6:7], 0, v[132:133]
	s_mov_b32 m0, s91
	s_nop 0
	global_load_lds_dwordx4 v[218:219], off
	s_waitcnt vmcnt(8)
	s_waitcnt lgkmcnt(0)
	s_setprio 1
	s_barrier
	v_mfma_f32_16x16x32_bf16 v[126:129], v[144:147], v[182:185], v[126:129]
	v_mfma_f32_16x16x32_bf16 v[122:125], v[152:155], v[182:185], v[122:125]
	v_mfma_f32_16x16x32_bf16 v[110:113], v[144:147], v[190:193], v[110:113]
	v_mfma_f32_16x16x32_bf16 v[106:109], v[152:155], v[190:193], v[106:109]
	v_mfma_f32_16x16x32_bf16 v[94:97], v[144:147], v[198:201], v[94:97]
	v_mfma_f32_16x16x32_bf16 v[90:93], v[152:155], v[198:201], v[90:93]
	v_mfma_f32_16x16x32_bf16 v[78:81], v[144:147], v[206:209], v[78:81]
	v_mfma_f32_16x16x32_bf16 v[74:77], v[152:155], v[206:209], v[74:77]
	v_mfma_f32_16x16x32_bf16 v[126:129], v[148:151], v[186:189], v[126:129]
	v_mfma_f32_16x16x32_bf16 v[122:125], v[156:159], v[186:189], v[122:125]
	v_mfma_f32_16x16x32_bf16 v[110:113], v[148:151], v[194:197], v[110:113]
	v_mfma_f32_16x16x32_bf16 v[106:109], v[156:159], v[194:197], v[106:109]
	v_mfma_f32_16x16x32_bf16 v[94:97], v[148:151], v[202:205], v[94:97]
	v_mfma_f32_16x16x32_bf16 v[90:93], v[156:159], v[202:205], v[90:93]
	v_mfma_f32_16x16x32_bf16 v[78:81], v[148:151], v[210:213], v[78:81]
	v_mfma_f32_16x16x32_bf16 v[74:77], v[156:159], v[210:213], v[74:77]
	v_mfma_f32_16x16x32_bf16 v[118:121], v[166:169], v[182:185], v[118:121]
	v_mfma_f32_16x16x32_bf16 v[114:117], v[174:177], v[182:185], v[114:117]
	v_mfma_f32_16x16x32_bf16 v[102:105], v[166:169], v[190:193], v[102:105]
	v_mfma_f32_16x16x32_bf16 v[98:101], v[174:177], v[190:193], v[98:101]
	v_mfma_f32_16x16x32_bf16 v[86:89], v[166:169], v[198:201], v[86:89]
	v_mfma_f32_16x16x32_bf16 v[82:85], v[174:177], v[198:201], v[82:85]
	v_mfma_f32_16x16x32_bf16 v[70:73], v[166:169], v[206:209], v[70:73]
	v_mfma_f32_16x16x32_bf16 v[66:69], v[174:177], v[206:209], v[66:69]
	v_mfma_f32_16x16x32_bf16 v[118:121], v[170:173], v[186:189], v[118:121]
	v_mfma_f32_16x16x32_bf16 v[114:117], v[178:181], v[186:189], v[114:117]
	v_mfma_f32_16x16x32_bf16 v[102:105], v[170:173], v[194:197], v[102:105]
	v_mfma_f32_16x16x32_bf16 v[98:101], v[178:181], v[194:197], v[98:101]
	v_mfma_f32_16x16x32_bf16 v[86:89], v[170:173], v[202:205], v[86:89]
	v_mfma_f32_16x16x32_bf16 v[82:85], v[178:181], v[202:205], v[82:85]
	v_mfma_f32_16x16x32_bf16 v[70:73], v[170:173], v[210:213], v[70:73]
	v_mfma_f32_16x16x32_bf16 v[66:69], v[178:181], v[210:213], v[66:69]
	s_barrier
; #define PG8_STAGE(bufoff, gbase, voff) do { _Pragma("unroll") for (int _i = 0; _i < 2; ++_i) \
;         __builtin_amdgcn_global_load_lds((const unsigned*)((const char*)(gbase) + (voff)[_i]), (LAS unsigned*)(lds + (bufoff) + ldsw + _i * 8192), 16, 0, 0); } while (0)
; #define PG8_LDA(dst, b, h) do { _Pragma("unroll") for (int m = 0; m < 4; ++m) _Pragma("unroll") for (int k = 0; k < 2; ++k) dst[m][k] = *(const LAS bf16x8*)(lds + PG8_SA(b, h) + aoff + m * 2048 + k * 1024); } while (0)
; #define PG8_MMA(ai, bj, At, Bt) do { __builtin_amdgcn_s_setprio(1); _Pragma("unroll") for (int m = 0; m < 4; ++m) _Pragma("unroll") for (int n = 0; n < 2; ++n) _Pragma("unroll") for (int k = 0; k < 2; ++k) \
;         acc[ai][bj][m][n] = __builtin_amdgcn_mfma_f32_16x16x32_bf16(Bt[n][k], At[m][k], acc[ai][bj][m][n], 0, 0, 0); __builtin_amdgcn_s_setprio(0); } while (0)
; #define PG8_WAIT_V(n) asm volatile("s_waitcnt vmcnt(" #n ")" ::: "memory")
; #define PG8_WAIT_L(n) asm volatile("s_waitcnt lgkmcnt(" #n ")" ::: "memory")
; #define PG8_BAR __builtin_amdgcn_s_barrier()
; #define PG8_SCHED __builtin_amdgcn_sched_barrier(0)
; template <class Epi, int AMODE>
; __device__ __forceinline__ void gemm_phase(LAS unsigned char* lds, const Gemm g, const StaticOrder& S, const Epi& E, int stagger_us, int tid_in) {
;     ...
;             PG8_LDA(At, 1, 1); PG8_STAGE(PG8_SB(1, 0), b3, voffB); PG8_STAGE(PG8_SB(1, 1), b3 + hstepB, voffB); PG8_STAGE(PG8_SA(1, 0), a3, voffA);
;             PG8_WAIT_V(8); PG8_WAIT_L(0); PG8_BAR; PG8_MMA(1, 0, At, B0); PG8_MMA(1, 1, At, B1); PG8_BAR; PG8_SCHED;
;         }
;         if (wr == 0) PG8_BAR;
	s_setprio 0
	s_add_i32 s6, s30, s66
	v_lshl_add_u64 v[140:141], v[140:141], 0, s[74:75]
	s_mov_b32 m0, s6
	ds_read_b128 v[182:185], v164 offset:49152
	ds_read_b128 v[186:189], v164 offset:50176
	ds_read_b128 v[190:193], v164 offset:51200
	ds_read_b128 v[194:197], v164 offset:52224
	ds_read_b128 v[198:201], v164 offset:53248
	ds_read_b128 v[202:205], v164 offset:54272
	ds_read_b128 v[206:209], v164 offset:55296
	ds_read_b128 v[210:213], v164 offset:56320
	global_load_lds_dwordx4 v[140:141], off
	s_add_i32 m0, s6, 0x2000
	s_add_u32 s4, s4, 0x80080
	v_lshl_add_u64 v[140:141], v[160:161], 0, s[74:75]
	s_addc_u32 s5, s5, 0
	s_add_i32 s6, s31, s66
	global_load_lds_dwordx4 v[140:141], off
	v_lshl_add_u64 v[140:141], s[4:5], 0, v[0:1]
	s_mov_b32 m0, s6
	s_nop 0
	global_load_lds_dwordx4 v[140:141], off
	v_lshl_add_u64 v[140:141], s[4:5], 0, v[130:131]
	s_add_i32 m0, s6, 0x2000
	s_nop 0
	global_load_lds_dwordx4 v[140:141], off
	v_lshl_add_u64 v[140:141], v[214:215], 0, s[74:75]
	s_mov_b32 m0, s95
	s_nop 0
	global_load_lds_dwordx4 v[140:141], off
	v_lshl_add_u64 v[140:141], v[216:217], 0, s[74:75]
	s_mov_b32 m0, s96
	s_nop 0
	global_load_lds_dwordx4 v[140:141], off
	s_waitcnt vmcnt(8)
	s_waitcnt lgkmcnt(0)
	s_setprio 1
	s_barrier
	v_mfma_f32_16x16x32_bf16 v[62:65], v[144:147], v[182:185], v[62:65]
	v_mfma_f32_16x16x32_bf16 v[58:61], v[152:155], v[182:185], v[58:61]
	v_mfma_f32_16x16x32_bf16 v[46:49], v[144:147], v[190:193], v[46:49]
	v_mfma_f32_16x16x32_bf16 v[42:45], v[152:155], v[190:193], v[42:45]
	v_mfma_f32_16x16x32_bf16 v[30:33], v[144:147], v[198:201], v[30:33]
	v_mfma_f32_16x16x32_bf16 v[26:29], v[152:155], v[198:201], v[26:29]
	v_mfma_f32_16x16x32_bf16 v[14:17], v[144:147], v[206:209], v[14:17]
	v_mfma_f32_16x16x32_bf16 v[10:13], v[152:155], v[206:209], v[10:13]
	v_mfma_f32_16x16x32_bf16 v[62:65], v[148:151], v[186:189], v[62:65]
	v_mfma_f32_16x16x32_bf16 v[58:61], v[156:159], v[186:189], v[58:61]
	v_mfma_f32_16x16x32_bf16 v[46:49], v[148:151], v[194:197], v[46:49]
	v_mfma_f32_16x16x32_bf16 v[42:45], v[156:159], v[194:197], v[42:45]
	v_mfma_f32_16x16x32_bf16 v[30:33], v[148:151], v[202:205], v[30:33]
	v_mfma_f32_16x16x32_bf16 v[26:29], v[156:159], v[202:205], v[26:29]
	v_mfma_f32_16x16x32_bf16 v[14:17], v[148:151], v[210:213], v[14:17]
	v_mfma_f32_16x16x32_bf16 v[10:13], v[156:159], v[210:213], v[10:13]
	v_mfma_f32_16x16x32_bf16 v[54:57], v[166:169], v[182:185], v[54:57]
	v_mfma_f32_16x16x32_bf16 v[50:53], v[174:177], v[182:185], v[50:53]
	v_mfma_f32_16x16x32_bf16 v[38:41], v[166:169], v[190:193], v[38:41]
	v_mfma_f32_16x16x32_bf16 v[34:37], v[174:177], v[190:193], v[34:37]
	v_mfma_f32_16x16x32_bf16 v[22:25], v[166:169], v[198:201], v[22:25]
	v_mfma_f32_16x16x32_bf16 v[18:21], v[174:177], v[198:201], v[18:21]
	v_mfma_f32_16x16x32_bf16 v[6:9], v[166:169], v[206:209], v[6:9]
	v_mfma_f32_16x16x32_bf16 v[2:5], v[174:177], v[206:209], v[2:5]
	v_mfma_f32_16x16x32_bf16 v[54:57], v[170:173], v[186:189], v[54:57]
	v_mfma_f32_16x16x32_bf16 v[50:53], v[178:181], v[186:189], v[50:53]
	v_mfma_f32_16x16x32_bf16 v[38:41], v[170:173], v[194:197], v[38:41]
	v_mfma_f32_16x16x32_bf16 v[34:37], v[178:181], v[194:197], v[34:37]
	v_mfma_f32_16x16x32_bf16 v[22:25], v[170:173], v[202:205], v[22:25]
	v_mfma_f32_16x16x32_bf16 v[18:21], v[178:181], v[202:205], v[18:21]
	v_mfma_f32_16x16x32_bf16 v[6:9], v[170:173], v[210:213], v[6:9]
	v_mfma_f32_16x16x32_bf16 v[2:5], v[178:181], v[210:213], v[2:5]
	s_barrier
	s_setprio 0
	s_add_i32 s29, s29, 2
	s_add_u32 s60, s60, 0x100
	s_addc_u32 s61, s61, 0
	s_add_u32 vcc_lo, vcc_lo, 0x100
	s_addc_u32 vcc_hi, vcc_hi, 0
	s_cmp_gt_u32 s29, 29
	s_cbranch_scc0 .LBB0_396
	s_and_b64 vcc, exec, s[46:47]
	s_cbranch_vccz .LBB0_399
	s_barrier

; #define PG8_STAGE(bufoff, gbase, voff) do { _Pragma("unroll") for (int _i = 0; _i < 2; ++_i) \
;         __builtin_amdgcn_global_load_lds((const unsigned*)((const char*)(gbase) + (voff)[_i]), (LAS unsigned*)(lds + (bufoff) + ldsw + _i * 8192), 16, 0, 0); } while (0)
; #define PG8_LDA(dst, b, h) do { _Pragma("unroll") for (int m = 0; m < 4; ++m) _Pragma("unroll") for (int k = 0; k < 2; ++k) dst[m][k] = *(const LAS bf16x8*)(lds + PG8_SA(b, h) + aoff + m * 2048 + k * 1024); } while (0)
; #define PG8_LDB(dst, b, h) do { _Pragma("unroll") for (int n = 0; n < 2; ++n) _Pragma("unroll") for (int k = 0; k < 2; ++k) dst[n][k] = *(const LAS bf16x8*)(lds + PG8_SB(b, h) + boff + n * 2048 + k * 1024); } while (0)
; #define PG8_MMA(ai, bj, At, Bt) do { __builtin_amdgcn_s_setprio(1); _Pragma("unroll") for (int m = 0; m < 4; ++m) _Pragma("unroll") for (int n = 0; n < 2; ++n) _Pragma("unroll") for (int k = 0; k < 2; ++k) \
;         acc[ai][bj][m][n] = __builtin_amdgcn_mfma_f32_16x16x32_bf16(Bt[n][k], At[m][k], acc[ai][bj][m][n], 0, 0, 0); __builtin_amdgcn_s_setprio(0); } while (0)
; #define PG8_BAR __builtin_amdgcn_s_barrier()
; template <class Epi, int AMODE>
; __device__ __forceinline__ void gemm_phase(LAS unsigned char* lds, const Gemm g, const StaticOrder& S, const Epi& E, int stagger_us, int tid_in) {
;     ...
;         const bool has_next = S.next(ui + 1, nxt);
;         const char* nA = has_next ? Abase + (size_t)nxt.pm * tstepA : cA; const char* nB = has_next ? (const char*)g.Bt + (size_t)nxt.pn * tstepB : cB;
;         for (int t = 0; t < nt; t += 2) {
;             const bool last = (t == nt - 2);
;             const char* a1 = cA + (size_t)(t + 1) * kstep;
;             const char* a2 = last ? nA : cA + (size_t)(t + 2) * kstep; const char* b2 = last ? nB : cB + (size_t)(t + 2) * kstep;
;             const char* a3 = a2 + kstep; const char* b3 = b2 + kstep;
;             PG8_LDB(B0, 0, 0); PG8_LDB(B1, 0, 1); PG8_SCHED; PG8_LDA(At, 0, 0); PG8_STAGE(PG8_SA(1, 1), a1 + hstepA, voffA);
;             PG8_WAIT_V(8); PG8_WAIT_L(0); PG8_BAR; PG8_MMA(0, 0, At, B0); PG8_MMA(0, 1, At, B1); PG8_BAR; PG8_SCHED;
;             PG8_LDA(At, 0, 1); PG8_STAGE(PG8_SB(0, 0), b2, voffB); PG8_STAGE(PG8_SB(0, 1), b2 + hstepB, voffB); PG8_STAGE(PG8_SA(0, 0), a2, voffA);
;             PG8_WAIT_V(8); PG8_WAIT_L(0); PG8_BAR; PG8_MMA(1, 0, At, B0); PG8_MMA(1, 1, At, B1); PG8_BAR; PG8_SCHED;
.LBB0_1199:
	s_add_u32 s4, s46, 0x100
	s_addc_u32 s5, s47, 0
	s_add_i32 s34, 0, 0x10000
	s_cmp_eq_u32 s31, 28
	s_cselect_b32 s95, s61, s5
	s_cselect_b32 s94, vcc_lo, s4
	s_cselect_b32 s7, s59, s30
	s_cselect_b32 s6, vcc_hi, s29
	s_add_i32 s35, 0, 0x14000
	v_add_u32_e32 v62, s34, v205
	v_add_u32_e32 v158, s35, v205
	ds_read_b128 v[50:53], v62
	ds_read_b128 v[54:57], v62 offset:1024
	ds_read_b128 v[58:61], v62 offset:2048
	ds_read_b128 v[62:65], v62 offset:3072
	ds_read_b128 v[146:149], v158
	ds_read_b128 v[150:153], v158 offset:1024
	ds_read_b128 v[154:157], v158 offset:2048
	ds_read_b128 v[158:161], v158 offset:3072
	v_lshl_add_u64 v[200:201], s[46:47], 0, v[176:177]
	s_add_i32 m0, s66, 0xc000
	ds_read_b128 v[162:165], v207
	ds_read_b128 v[166:169], v207 offset:1024
	ds_read_b128 v[170:173], v207 offset:2048
	ds_read_b128 v[180:183], v207 offset:3072
	ds_read_b128 v[184:187], v207 offset:4096
	ds_read_b128 v[188:191], v207 offset:5120
	ds_read_b128 v[192:195], v207 offset:6144
	ds_read_b128 v[196:199], v207 offset:7168
	global_load_lds_dwordx4 v[200:201], off
	v_lshl_add_u64 v[200:201], s[46:47], 0, v[178:179]
	s_add_i32 m0, s66, 0xe000
	s_nop 0
	global_load_lds_dwordx4 v[200:201], off
	s_waitcnt vmcnt(8)
	s_waitcnt lgkmcnt(0)
	s_setprio 1
	s_barrier
	v_mfma_f32_16x16x32_bf16 v[142:145], v[50:53], v[162:165], v[142:145]
	v_mfma_f32_16x16x32_bf16 v[138:141], v[58:61], v[162:165], v[138:141]
	v_mfma_f32_16x16x32_bf16 v[126:129], v[50:53], v[170:173], v[126:129]
	v_mfma_f32_16x16x32_bf16 v[122:125], v[58:61], v[170:173], v[122:125]
	v_mfma_f32_16x16x32_bf16 v[110:113], v[50:53], v[184:187], v[110:113]
	v_mfma_f32_16x16x32_bf16 v[106:109], v[58:61], v[184:187], v[106:109]
	v_mfma_f32_16x16x32_bf16 v[94:97], v[50:53], v[192:195], v[94:97]
	v_mfma_f32_16x16x32_bf16 v[90:93], v[58:61], v[192:195], v[90:93]
	v_mfma_f32_16x16x32_bf16 v[142:145], v[54:57], v[166:169], v[142:145]
	v_mfma_f32_16x16x32_bf16 v[138:141], v[62:65], v[166:169], v[138:141]
	v_mfma_f32_16x16x32_bf16 v[126:129], v[54:57], v[180:183], v[126:129]
	v_mfma_f32_16x16x32_bf16 v[122:125], v[62:65], v[180:183], v[122:125]
	v_mfma_f32_16x16x32_bf16 v[110:113], v[54:57], v[188:191], v[110:113]
	v_mfma_f32_16x16x32_bf16 v[106:109], v[62:65], v[188:191], v[106:109]
	v_mfma_f32_16x16x32_bf16 v[94:97], v[54:57], v[196:199], v[94:97]
	v_mfma_f32_16x16x32_bf16 v[90:93], v[62:65], v[196:199], v[90:93]
	v_mfma_f32_16x16x32_bf16 v[134:137], v[146:149], v[162:165], v[134:137]
	v_mfma_f32_16x16x32_bf16 v[130:133], v[154:157], v[162:165], v[130:133]
	v_mfma_f32_16x16x32_bf16 v[118:121], v[146:149], v[170:173], v[118:121]
	v_mfma_f32_16x16x32_bf16 v[114:117], v[154:157], v[170:173], v[114:117]
	v_mfma_f32_16x16x32_bf16 v[102:105], v[146:149], v[184:187], v[102:105]
	v_mfma_f32_16x16x32_bf16 v[98:101], v[154:157], v[184:187], v[98:101]
	v_mfma_f32_16x16x32_bf16 v[86:89], v[146:149], v[192:195], v[86:89]
	v_mfma_f32_16x16x32_bf16 v[82:85], v[154:157], v[192:195], v[82:85]
	v_mfma_f32_16x16x32_bf16 v[134:137], v[150:153], v[166:169], v[134:137]
	v_mfma_f32_16x16x32_bf16 v[130:133], v[158:161], v[166:169], v[130:133]
	v_mfma_f32_16x16x32_bf16 v[118:121], v[150:153], v[180:183], v[118:121]
	v_mfma_f32_16x16x32_bf16 v[114:117], v[158:161], v[180:183], v[114:117]
	v_mfma_f32_16x16x32_bf16 v[102:105], v[150:153], v[188:191], v[102:105]
	v_mfma_f32_16x16x32_bf16 v[98:101], v[158:161], v[188:191], v[98:101]
	v_mfma_f32_16x16x32_bf16 v[86:89], v[150:153], v[196:199], v[86:89]
	v_mfma_f32_16x16x32_bf16 v[82:85], v[158:161], v[196:199], v[82:85]
	s_barrier
	s_setprio 0
	s_add_i32 s34, s34, s13
	v_lshl_add_u64 v[200:201], s[6:7], 0, v[0:1]
	s_mov_b32 m0, s34
	ds_read_b128 v[162:165], v207 offset:16384
	ds_read_b128 v[166:169], v207 offset:17408
	ds_read_b128 v[170:173], v207 offset:18432
	ds_read_b128 v[180:183], v207 offset:19456
	ds_read_b128 v[184:187], v207 offset:20480
	ds_read_b128 v[188:191], v207 offset:21504
	ds_read_b128 v[192:195], v207 offset:22528
	ds_read_b128 v[196:199], v207 offset:23552
	global_load_lds_dwordx4 v[200:201], off
	s_add_i32 m0, s34, 0x2000
	s_add_u32 s46, s6, 0x80000
	v_lshl_add_u64 v[202:203], s[6:7], 0, v[174:175]
	s_addc_u32 s47, s7, 0
	s_add_i32 s34, s35, s13
	global_load_lds_dwordx4 v[202:203], off
	v_lshl_add_u64 v[208:209], s[46:47], 0, v[0:1]
	s_mov_b32 m0, s34
	v_lshl_add_u64 v[210:211], s[94:95], 0, v[174:175]
	global_load_lds_dwordx4 v[208:209], off
	v_lshl_add_u64 v[208:209], s[46:47], 0, v[174:175]
	s_add_i32 m0, s34, 0x2000
	s_nop 0
	global_load_lds_dwordx4 v[208:209], off
	v_lshl_add_u64 v[208:209], s[94:95], 0, v[0:1]
	s_mov_b32 m0, s66
	s_nop 0
	global_load_lds_dwordx4 v[208:209], off
	s_mov_b32 m0, s67
	s_nop 0
	global_load_lds_dwordx4 v[210:211], off
	s_waitcnt vmcnt(8)
	s_waitcnt lgkmcnt(0)
	s_setprio 1
	s_barrier
; #define PG8_STAGE(bufoff, gbase, voff) do { _Pragma("unroll") for (int _i = 0; _i < 2; ++_i) \
;         __builtin_amdgcn_global_load_lds((const unsigned*)((const char*)(gbase) + (voff)[_i]), (LAS unsigned*)(lds + (bufoff) + ldsw + _i * 8192), 16, 0, 0); } while (0)
; #define PG8_LDA(dst, b, h) do { _Pragma("unroll") for (int m = 0; m < 4; ++m) _Pragma("unroll") for (int k = 0; k < 2; ++k) dst[m][k] = *(const LAS bf16x8*)(lds + PG8_SA(b, h) + aoff + m * 2048 + k * 1024); } while (0)
; #define PG8_LDB(dst, b, h) do { _Pragma("unroll") for (int n = 0; n < 2; ++n) _Pragma("unroll") for (int k = 0; k < 2; ++k) dst[n][k] = *(const LAS bf16x8*)(lds + PG8_SB(b, h) + boff + n * 2048 + k * 1024); } while (0)
; #define PG8_MMA(ai, bj, At, Bt) do { __builtin_amdgcn_s_setprio(1); _Pragma("unroll") for (int m = 0; m < 4; ++m) _Pragma("unroll") for (int n = 0; n < 2; ++n) _Pragma("unroll") for (int k = 0; k < 2; ++k) \
;         acc[ai][bj][m][n] = __builtin_amdgcn_mfma_f32_16x16x32_bf16(Bt[n][k], At[m][k], acc[ai][bj][m][n], 0, 0, 0); __builtin_amdgcn_s_setprio(0); } while (0)
; #define PG8_WAIT_V(n) asm volatile("s_waitcnt vmcnt(" #n ")" ::: "memory")
; #define PG8_WAIT_L(n) asm volatile("s_waitcnt lgkmcnt(" #n ")" ::: "memory")
; #define PG8_BAR __builtin_amdgcn_s_barrier()
; #define PG8_SCHED __builtin_amdgcn_sched_barrier(0)
; template <class Epi, int AMODE>
; __device__ __forceinline__ void gemm_phase(LAS unsigned char* lds, const Gemm g, const StaticOrder& S, const Epi& E, int stagger_us, int tid_in) {
;     ...
;             PG8_WAIT_V(8); PG8_WAIT_L(0); PG8_BAR; PG8_MMA(1, 0, At, B0); PG8_MMA(1, 1, At, B1); PG8_BAR; PG8_SCHED;
;             PG8_LDB(B0, 1, 0); PG8_LDB(B1, 1, 1); PG8_SCHED; PG8_LDA(At, 1, 0); PG8_STAGE(PG8_SA(0, 1), a2 + hstepA, voffA);
;             PG8_WAIT_V(8); PG8_WAIT_L(0); PG8_BAR; PG8_MMA(0, 0, At, B0); PG8_MMA(0, 1, At, B1); PG8_BAR; PG8_SCHED;
	v_mfma_f32_16x16x32_bf16 v[78:81], v[50:53], v[162:165], v[78:81]
	v_mfma_f32_16x16x32_bf16 v[74:77], v[58:61], v[162:165], v[74:77]
	v_mfma_f32_16x16x32_bf16 v[46:49], v[50:53], v[170:173], v[46:49]
	v_mfma_f32_16x16x32_bf16 v[42:45], v[58:61], v[170:173], v[42:45]
	v_mfma_f32_16x16x32_bf16 v[30:33], v[50:53], v[184:187], v[30:33]
	v_mfma_f32_16x16x32_bf16 v[26:29], v[58:61], v[184:187], v[26:29]
	v_mfma_f32_16x16x32_bf16 v[14:17], v[50:53], v[192:195], v[14:17]
	v_mfma_f32_16x16x32_bf16 v[10:13], v[58:61], v[192:195], v[10:13]
	v_mfma_f32_16x16x32_bf16 v[78:81], v[54:57], v[166:169], v[78:81]
	v_mfma_f32_16x16x32_bf16 v[74:77], v[62:65], v[166:169], v[74:77]
	v_mfma_f32_16x16x32_bf16 v[46:49], v[54:57], v[180:183], v[46:49]
	v_mfma_f32_16x16x32_bf16 v[42:45], v[62:65], v[180:183], v[42:45]
	v_mfma_f32_16x16x32_bf16 v[30:33], v[54:57], v[188:191], v[30:33]
	v_mfma_f32_16x16x32_bf16 v[26:29], v[62:65], v[188:191], v[26:29]
	v_mfma_f32_16x16x32_bf16 v[14:17], v[54:57], v[196:199], v[14:17]
	v_mfma_f32_16x16x32_bf16 v[10:13], v[62:65], v[196:199], v[10:13]
	v_mfma_f32_16x16x32_bf16 v[38:41], v[146:149], v[170:173], v[38:41]
	v_mfma_f32_16x16x32_bf16 v[34:37], v[154:157], v[170:173], v[34:37]
	v_mfma_f32_16x16x32_bf16 v[22:25], v[146:149], v[184:187], v[22:25]
	v_mfma_f32_16x16x32_bf16 v[18:21], v[154:157], v[184:187], v[18:21]
	v_mfma_f32_16x16x32_bf16 v[6:9], v[146:149], v[192:195], v[6:9]
	v_mfma_f32_16x16x32_bf16 v[2:5], v[154:157], v[192:195], v[2:5]
	v_mfma_f32_16x16x32_bf16 v[50:53], v[146:149], v[162:165], v[70:73]
	v_mfma_f32_16x16x32_bf16 v[54:57], v[154:157], v[162:165], v[66:69]
	v_mfma_f32_16x16x32_bf16 v[38:41], v[150:153], v[180:183], v[38:41]
	v_mfma_f32_16x16x32_bf16 v[34:37], v[158:161], v[180:183], v[34:37]
	v_mfma_f32_16x16x32_bf16 v[22:25], v[150:153], v[188:191], v[22:25]
	v_mfma_f32_16x16x32_bf16 v[18:21], v[158:161], v[188:191], v[18:21]
	v_mfma_f32_16x16x32_bf16 v[6:9], v[150:153], v[196:199], v[6:9]
	v_mfma_f32_16x16x32_bf16 v[2:5], v[158:161], v[196:199], v[2:5]
	v_mfma_f32_16x16x32_bf16 v[50:53], v[150:153], v[166:169], v[50:53]
	v_mfma_f32_16x16x32_bf16 v[54:57], v[158:161], v[166:169], v[54:57]
	s_barrier
	s_setprio 0
	s_add_i32 s34, 0, 0x18000
	s_add_i32 s35, 0, 0x1c000
	v_add_u32_e32 v70, s34, v205
	v_add_u32_e32 v158, s35, v205
	ds_read_b128 v[58:61], v70
	ds_read_b128 v[62:65], v70 offset:1024
	ds_read_b128 v[66:69], v70 offset:2048
	ds_read_b128 v[70:73], v70 offset:3072
	ds_read_b128 v[146:149], v158
	ds_read_b128 v[150:153], v158 offset:1024
	ds_read_b128 v[154:157], v158 offset:2048
	ds_read_b128 v[158:161], v158 offset:3072
	s_add_u32 s46, s94, 0x80000
	s_addc_u32 s47, s95, 0
	s_mov_b32 m0, s69
	v_lshl_add_u64 v[212:213], s[46:47], 0, v[0:1]
	ds_read_b128 v[162:165], v207 offset:32768
	ds_read_b128 v[166:169], v207 offset:33792
	ds_read_b128 v[170:173], v207 offset:34816
	ds_read_b128 v[180:183], v207 offset:35840
	ds_read_b128 v[184:187], v207 offset:36864
	ds_read_b128 v[188:191], v207 offset:37888
	ds_read_b128 v[192:195], v207 offset:38912
	ds_read_b128 v[196:199], v207 offset:39936
	global_load_lds_dwordx4 v[212:213], off
	v_lshl_add_u64 v[212:213], s[46:47], 0, v[174:175]
	s_mov_b32 m0, s72
	s_nop 0
	global_load_lds_dwordx4 v[212:213], off
	s_waitcnt vmcnt(8)
	s_waitcnt lgkmcnt(0)
	s_setprio 1
	s_barrier
	v_mfma_f32_16x16x32_bf16 v[142:145], v[58:61], v[162:165], v[142:145]
	v_mfma_f32_16x16x32_bf16 v[138:141], v[66:69], v[162:165], v[138:141]
	v_mfma_f32_16x16x32_bf16 v[126:129], v[58:61], v[170:173], v[126:129]
	v_mfma_f32_16x16x32_bf16 v[122:125], v[66:69], v[170:173], v[122:125]
	v_mfma_f32_16x16x32_bf16 v[110:113], v[58:61], v[184:187], v[110:113]
	v_mfma_f32_16x16x32_bf16 v[106:109], v[66:69], v[184:187], v[106:109]
	v_mfma_f32_16x16x32_bf16 v[94:97], v[58:61], v[192:195], v[94:97]
	v_mfma_f32_16x16x32_bf16 v[90:93], v[66:69], v[192:195], v[90:93]
	v_mfma_f32_16x16x32_bf16 v[142:145], v[62:65], v[166:169], v[142:145]
	v_mfma_f32_16x16x32_bf16 v[138:141], v[70:73], v[166:169], v[138:141]
	v_mfma_f32_16x16x32_bf16 v[126:129], v[62:65], v[180:183], v[126:129]
	v_mfma_f32_16x16x32_bf16 v[122:125], v[70:73], v[180:183], v[122:125]
	v_mfma_f32_16x16x32_bf16 v[110:113], v[62:65], v[188:191], v[110:113]
	v_mfma_f32_16x16x32_bf16 v[106:109], v[70:73], v[188:191], v[106:109]
	v_mfma_f32_16x16x32_bf16 v[94:97], v[62:65], v[196:199], v[94:97]
	v_mfma_f32_16x16x32_bf16 v[90:93], v[70:73], v[196:199], v[90:93]
	v_mfma_f32_16x16x32_bf16 v[134:137], v[146:149], v[162:165], v[134:137]
	v_mfma_f32_16x16x32_bf16 v[130:133], v[154:157], v[162:165], v[130:133]
	v_mfma_f32_16x16x32_bf16 v[118:121], v[146:149], v[170:173], v[118:121]
	v_mfma_f32_16x16x32_bf16 v[114:117], v[154:157], v[170:173], v[114:117]
	v_mfma_f32_16x16x32_bf16 v[102:105], v[146:149], v[184:187], v[102:105]
	v_mfma_f32_16x16x32_bf16 v[98:101], v[154:157], v[184:187], v[98:101]
	v_mfma_f32_16x16x32_bf16 v[86:89], v[146:149], v[192:195], v[86:89]
	v_mfma_f32_16x16x32_bf16 v[82:85], v[154:157], v[192:195], v[82:85]
	v_mfma_f32_16x16x32_bf16 v[134:137], v[150:153], v[166:169], v[134:137]
	v_mfma_f32_16x16x32_bf16 v[130:133], v[158:161], v[166:169], v[130:133]
	v_mfma_f32_16x16x32_bf16 v[118:121], v[150:153], v[180:183], v[118:121]
	v_mfma_f32_16x16x32_bf16 v[114:117], v[158:161], v[180:183], v[114:117]
	v_mfma_f32_16x16x32_bf16 v[102:105], v[150:153], v[188:191], v[102:105]
	v_mfma_f32_16x16x32_bf16 v[98:101], v[158:161], v[188:191], v[98:101]
	v_mfma_f32_16x16x32_bf16 v[86:89], v[150:153], v[196:199], v[86:89]
	v_mfma_f32_16x16x32_bf16 v[82:85], v[158:161], v[196:199], v[82:85]
	s_barrier
; #define PG8_STAGE(bufoff, gbase, voff) do { _Pragma("unroll") for (int _i = 0; _i < 2; ++_i) \
;         __builtin_amdgcn_global_load_lds((const unsigned*)((const char*)(gbase) + (voff)[_i]), (LAS unsigned*)(lds + (bufoff) + ldsw + _i * 8192), 16, 0, 0); } while (0)
; #define PG8_LDA(dst, b, h) do { _Pragma("unroll") for (int m = 0; m < 4; ++m) _Pragma("unroll") for (int k = 0; k < 2; ++k) dst[m][k] = *(const LAS bf16x8*)(lds + PG8_SA(b, h) + aoff + m * 2048 + k * 1024); } while (0)
; #define PG8_MMA(ai, bj, At, Bt) do { __builtin_amdgcn_s_setprio(1); _Pragma("unroll") for (int m = 0; m < 4; ++m) _Pragma("unroll") for (int n = 0; n < 2; ++n) _Pragma("unroll") for (int k = 0; k < 2; ++k) \
;         acc[ai][bj][m][n] = __builtin_amdgcn_mfma_f32_16x16x32_bf16(Bt[n][k], At[m][k], acc[ai][bj][m][n], 0, 0, 0); __builtin_amdgcn_s_setprio(0); } while (0)
; #define PG8_WAIT_V(n) asm volatile("s_waitcnt vmcnt(" #n ")" ::: "memory")
; #define PG8_WAIT_L(n) asm volatile("s_waitcnt lgkmcnt(" #n ")" ::: "memory")
; #define PG8_BAR __builtin_amdgcn_s_barrier()
; #define PG8_SCHED __builtin_amdgcn_sched_barrier(0)
; template <class Epi, int AMODE>
; __device__ __forceinline__ void gemm_phase(LAS unsigned char* lds, const Gemm g, const StaticOrder& S, const Epi& E, int stagger_us, int tid_in) {
;     ...
;             PG8_LDA(At, 1, 1); PG8_STAGE(PG8_SB(1, 0), b3, voffB); PG8_STAGE(PG8_SB(1, 1), b3 + hstepB, voffB); PG8_STAGE(PG8_SA(1, 0), a3, voffA);
;             PG8_WAIT_V(8); PG8_WAIT_L(0); PG8_BAR; PG8_MMA(1, 0, At, B0); PG8_MMA(1, 1, At, B1); PG8_BAR; PG8_SCHED;
;         }
;         if (wr == 0) PG8_BAR;
	s_setprio 0
	s_add_i32 s34, s34, s13
	v_lshl_add_u64 v[200:201], v[200:201], 0, s[74:75]
	s_mov_b32 m0, s34
	ds_read_b128 v[162:165], v207 offset:49152
	ds_read_b128 v[166:169], v207 offset:50176
	ds_read_b128 v[170:173], v207 offset:51200
	ds_read_b128 v[180:183], v207 offset:52224
	ds_read_b128 v[184:187], v207 offset:53248
	ds_read_b128 v[188:191], v207 offset:54272
	ds_read_b128 v[192:195], v207 offset:55296
	ds_read_b128 v[196:199], v207 offset:56320
	global_load_lds_dwordx4 v[200:201], off
	s_add_i32 m0, s34, 0x2000
	s_add_u32 s6, s6, 0x80080
	v_lshl_add_u64 v[200:201], v[202:203], 0, s[74:75]
	s_addc_u32 s7, s7, 0
	s_add_i32 s34, s35, s13
	global_load_lds_dwordx4 v[200:201], off
	v_lshl_add_u64 v[200:201], s[6:7], 0, v[0:1]
	s_mov_b32 m0, s34
	s_nop 0
	global_load_lds_dwordx4 v[200:201], off
	v_lshl_add_u64 v[200:201], s[6:7], 0, v[174:175]
	s_add_i32 m0, s34, 0x2000
	s_nop 0
	global_load_lds_dwordx4 v[200:201], off
	v_lshl_add_u64 v[200:201], v[208:209], 0, s[74:75]
	s_mov_b32 m0, s91
	s_nop 0
	global_load_lds_dwordx4 v[200:201], off
	v_lshl_add_u64 v[200:201], v[210:211], 0, s[74:75]
	s_mov_b32 m0, s96
	s_nop 0
	global_load_lds_dwordx4 v[200:201], off
	s_waitcnt vmcnt(8)
	s_waitcnt lgkmcnt(0)
	s_setprio 1
	s_barrier
	v_mfma_f32_16x16x32_bf16 v[78:81], v[58:61], v[162:165], v[78:81]
	v_mfma_f32_16x16x32_bf16 v[74:77], v[66:69], v[162:165], v[74:77]
	v_mfma_f32_16x16x32_bf16 v[46:49], v[58:61], v[170:173], v[46:49]
	v_mfma_f32_16x16x32_bf16 v[42:45], v[66:69], v[170:173], v[42:45]
	v_mfma_f32_16x16x32_bf16 v[30:33], v[58:61], v[184:187], v[30:33]
	v_mfma_f32_16x16x32_bf16 v[26:29], v[66:69], v[184:187], v[26:29]
	v_mfma_f32_16x16x32_bf16 v[14:17], v[58:61], v[192:195], v[14:17]
	v_mfma_f32_16x16x32_bf16 v[10:13], v[66:69], v[192:195], v[10:13]
	v_mfma_f32_16x16x32_bf16 v[78:81], v[62:65], v[166:169], v[78:81]
	v_mfma_f32_16x16x32_bf16 v[74:77], v[70:73], v[166:169], v[74:77]
	v_mfma_f32_16x16x32_bf16 v[46:49], v[62:65], v[180:183], v[46:49]
	v_mfma_f32_16x16x32_bf16 v[42:45], v[70:73], v[180:183], v[42:45]
	v_mfma_f32_16x16x32_bf16 v[30:33], v[62:65], v[188:191], v[30:33]
	v_mfma_f32_16x16x32_bf16 v[26:29], v[70:73], v[188:191], v[26:29]
	v_mfma_f32_16x16x32_bf16 v[14:17], v[62:65], v[196:199], v[14:17]
	v_mfma_f32_16x16x32_bf16 v[10:13], v[70:73], v[196:199], v[10:13]
	v_mfma_f32_16x16x32_bf16 v[50:53], v[146:149], v[162:165], v[50:53]
	v_mfma_f32_16x16x32_bf16 v[70:73], v[150:153], v[166:169], v[50:53]
	v_mfma_f32_16x16x32_bf16 v[50:53], v[154:157], v[162:165], v[54:57]
	v_mfma_f32_16x16x32_bf16 v[38:41], v[146:149], v[170:173], v[38:41]
	v_mfma_f32_16x16x32_bf16 v[34:37], v[154:157], v[170:173], v[34:37]
	v_mfma_f32_16x16x32_bf16 v[22:25], v[146:149], v[184:187], v[22:25]
	v_mfma_f32_16x16x32_bf16 v[18:21], v[154:157], v[184:187], v[18:21]
	v_mfma_f32_16x16x32_bf16 v[6:9], v[146:149], v[192:195], v[6:9]
	v_mfma_f32_16x16x32_bf16 v[2:5], v[154:157], v[192:195], v[2:5]
	v_mfma_f32_16x16x32_bf16 v[66:69], v[158:161], v[166:169], v[50:53]
	v_mfma_f32_16x16x32_bf16 v[38:41], v[150:153], v[180:183], v[38:41]
	v_mfma_f32_16x16x32_bf16 v[34:37], v[158:161], v[180:183], v[34:37]
	v_mfma_f32_16x16x32_bf16 v[22:25], v[150:153], v[188:191], v[22:25]
	v_mfma_f32_16x16x32_bf16 v[18:21], v[158:161], v[188:191], v[18:21]
	v_mfma_f32_16x16x32_bf16 v[6:9], v[150:153], v[196:199], v[6:9]
	v_mfma_f32_16x16x32_bf16 v[2:5], v[158:161], v[196:199], v[2:5]
	s_barrier
	s_setprio 0
	s_add_i32 s31, s31, 2
	s_add_u32 s29, s29, 0x100
	s_addc_u32 s30, s30, 0
	s_cmp_gt_u32 s31, 29
	s_mov_b64 s[46:47], s[4:5]
	s_cbranch_scc0 .LBB0_1199
	s_and_b64 vcc, exec, s[56:57]
	s_cbranch_vccz .LBB0_1202
	s_barrier

; #define PG8_STAGE(bufoff, gbase, voff) do { _Pragma("unroll") for (int _i = 0; _i < 2; ++_i) \
;         __builtin_amdgcn_global_load_lds((const unsigned*)((const char*)(gbase) + (voff)[_i]), (LAS unsigned*)(lds + (bufoff) + ldsw + _i * 8192), 16, 0, 0); } while (0)
; #define PG8_WAIT_V(n) asm volatile("s_waitcnt vmcnt(" #n ")" ::: "memory")
; #define PG8_WAIT_L(n) asm volatile("s_waitcnt lgkmcnt(" #n ")" ::: "memory")
; #define PG8_BAR __builtin_amdgcn_s_barrier()
; template <class Epi, int AMODE>
; __device__ __forceinline__ void gemm_phase(LAS unsigned char* lds, const Gemm g, const StaticOrder& S, const Epi& E, int stagger_us, int tid_in) {
;     ...
;         const bool has_next = S.next(ui + 1, nxt);
;         const char* nA = has_next ? Abase + (size_t)nxt.pm * tstepA : cA; const char* nB = has_next ? (const char*)g.Bt + (size_t)nxt.pn * tstepB : cB;
;         for (int t = 0; t < nt; t += 2) {
;             const bool last = (t == nt - 2);
;             const char* a1 = cA + (size_t)(t + 1) * kstep;
;             const char* a2 = last ? nA : cA + (size_t)(t + 2) * kstep; const char* b2 = last ? nB : cB + (size_t)(t + 2) * kstep;
;             const char* a3 = a2 + kstep; const char* b3 = b2 + kstep;
;             PG8_LDB(B0, 0, 0); PG8_LDB(B1, 0, 1); PG8_SCHED; PG8_LDA(At, 0, 0); PG8_STAGE(PG8_SA(1, 1), a1 + hstepA, voffA);
;             PG8_WAIT_V(8); PG8_WAIT_L(0); PG8_BAR; PG8_MMA(0, 0, At, B0); PG8_MMA(0, 1, At, B1); PG8_BAR; PG8_SCHED;
;     __device__ __forceinline__ void operator()(f32x4 (&acc)[2][2][4][2], const Unit& u, int wr, int wc, int fr, int fq) const {
;     ...
;         const int tok0 = 252 * u.pm + 126 * wr - 1;
;         {
;             const int tq = tok0 + 8 * fr; const int tA = tq < 0 ? 0 : (tq > TOK - 1 ? TOK - 1 : tq), tB = (tq + 7) > TOK - 1 ? TOK - 1 : (tq + 7);
;             const int bA = batch_of(tA), bB = batch_of(tB); const bool same = __all(bA == bB);
;             const float* bp0 = bias + 256 * u.pn + 32 * wc + 8 * fq;
;             f32x4 bvA[2][2]; float sq[8];
; #pragma unroll
;             for (int am = 0; am < 8; ++am) { int tok = tq + am; tok = tok < 0 ? 0 : (tok > TOK - 1 ? TOK - 1 : tok); sq[am] = LDG(float, ssq + tok); }
; #pragma unroll
;             for (int bj = 0; bj < 2; ++bj)
; #pragma unroll
;                 for (int n = 0; n < 2; ++n) bvA[bj][n] = LDG(f32x4, bp0 + (size_t)bA * (2 * DFF) + bj * HALF + 4 * n);
.LBB0_1298:
	s_ashr_i32 s47, s46, 31
	s_lshl_b64 s[6:7], s[46:47], 20
	s_add_u32 s96, s9, s6
	s_addc_u32 s97, s72, s7
	s_and_b64 s[6:7], s[42:43], exec
	s_cselect_b32 s27, s97, s5
	s_cselect_b32 s28, s96, s4
	s_add_u32 s29, s4, 0x100
	v_mov_b32_e32 v2, 0
	s_addc_u32 s30, s5, 0
	s_mov_b32 s31, -2
	s_mul_i32 s6, s26, 0xfc
	v_add_u32_e32 v222, s6, v197
	v_med3_i32 v240, v222, 0, v238
	v_add_u32_e32 v241, 0xffffe000, v240
	v_lshrrev_b32_e32 v241, 12, v241
	v_add_u32_e32 v241, 4, v241
	v_lshrrev_b32_e32 v242, 11, v240
	v_mov_b32_e32 v243, 0x2000
	v_cmp_gt_i32_e64 s[6:7], v243, v222
	s_nop 1
	v_cndmask_b32_e64 v241, v241, v242, s[6:7]
	s_lshl_b32 s6, s92, 8
	s_ashr_i32 s7, s6, 31
	v_lshl_add_u64 v[236:237], s[6:7], 2, v[184:185]
	v_mad_u64_u32 v[236:237], s[6:7], v241, s15, v[236:237]
	v_med3_i32 v224, v222, 0, v238
	v_lshlrev_b32_e32 v224, 2, v224
	global_load_dword v224, v224, s[56:57]
	v_add_u32_e32 v228, 1, v222
	v_med3_i32 v228, v228, 0, v238
	v_lshlrev_b32_e32 v228, 2, v228
	global_load_dword v228, v228, s[56:57]
	v_add_u32_e32 v231, 2, v222
	v_med3_i32 v231, v231, 0, v238
	v_lshlrev_b32_e32 v231, 2, v231
	global_load_dword v231, v231, s[56:57]
	v_add_u32_e32 v233, 3, v222
	v_med3_i32 v233, v233, 0, v238
	v_lshlrev_b32_e32 v233, 2, v233
	global_load_dword v233, v233, s[56:57]
	v_add_u32_e32 v234, 4, v222
	v_med3_i32 v234, v234, 0, v238
	v_lshlrev_b32_e32 v234, 2, v234
	global_load_dword v234, v234, s[56:57]
	v_add_u32_e32 v239, 5, v222
	v_med3_i32 v239, v239, 0, v238
	v_lshlrev_b32_e32 v239, 2, v239
	global_load_dword v239, v239, s[56:57]
	v_add_u32_e32 v252, 6, v222
	v_med3_i32 v252, v252, 0, v238
	v_lshlrev_b32_e32 v252, 2, v252
	global_load_dword v252, v252, s[56:57]
	v_add_u32_e32 v253, 7, v222
	v_med3_i32 v253, v253, 0, v238
	v_lshlrev_b32_e32 v253, 2, v253
	global_load_dword v253, v253, s[56:57]
	global_load_dwordx4 v[240:243], v[236:237], off
	global_load_dwordx4 v[244:247], v[236:237], off offset:16
	global_load_dwordx4 v[248:251], v[236:237], off offset:512
	global_load_dwordx2 v[222:223], v[236:237], off offset:528
	s_nop 0
	global_load_dwordx2 v[236:237], v[236:237], off offset:536
	v_mov_b32_e32 v3, v2
	v_mov_b32_e32 v4, v2
	v_mov_b32_e32 v5, v2
	v_mov_b32_e32 v14, v2
	v_mov_b32_e32 v15, v2
	v_mov_b32_e32 v16, v2
	v_mov_b32_e32 v17, v2
	v_mov_b32_e32 v10, v2
	v_mov_b32_e32 v11, v2
	v_mov_b32_e32 v12, v2
	v_mov_b32_e32 v13, v2
	v_mov_b32_e32 v26, v2
	v_mov_b32_e32 v27, v2
	v_mov_b32_e32 v28, v2
	v_mov_b32_e32 v29, v2
	v_mov_b32_e32 v6, v2
	v_mov_b32_e32 v7, v2
	v_mov_b32_e32 v8, v2
	v_mov_b32_e32 v9, v2
	v_mov_b32_e32 v42, v2
	v_mov_b32_e32 v43, v2
	v_mov_b32_e32 v44, v2
	v_mov_b32_e32 v45, v2
	v_mov_b32_e32 v30, v2
	v_mov_b32_e32 v31, v2
	v_mov_b32_e32 v32, v2
	v_mov_b32_e32 v33, v2
	v_mov_b32_e32 v58, v2
	v_mov_b32_e32 v59, v2
	v_mov_b32_e32 v60, v2
	v_mov_b32_e32 v61, v2
	v_mov_b32_e32 v74, v2
	v_mov_b32_e32 v75, v2
	v_mov_b32_e32 v76, v2
	v_mov_b32_e32 v77, v2
	v_mov_b32_e32 v22, v2
	v_mov_b32_e32 v23, v2
	v_mov_b32_e32 v24, v2
	v_mov_b32_e32 v25, v2
	v_mov_b32_e32 v34, v2
	v_mov_b32_e32 v35, v2
	v_mov_b32_e32 v36, v2
	v_mov_b32_e32 v37, v2
	v_mov_b32_e32 v18, v2
	v_mov_b32_e32 v19, v2
	v_mov_b32_e32 v20, v2
	v_mov_b32_e32 v21, v2
	v_mov_b32_e32 v50, v2
	v_mov_b32_e32 v51, v2
	v_mov_b32_e32 v52, v2
	v_mov_b32_e32 v53, v2
	v_mov_b32_e32 v38, v2
	v_mov_b32_e32 v39, v2
	v_mov_b32_e32 v40, v2
	v_mov_b32_e32 v41, v2
	v_mov_b32_e32 v46, v2
	v_mov_b32_e32 v47, v2
	v_mov_b32_e32 v48, v2
	v_mov_b32_e32 v49, v2
	v_mov_b32_e32 v54, v2
	v_mov_b32_e32 v55, v2
	v_mov_b32_e32 v56, v2
	v_mov_b32_e32 v57, v2
	v_mov_b32_e32 v66, v2
	v_mov_b32_e32 v67, v2
	v_mov_b32_e32 v68, v2
	v_mov_b32_e32 v69, v2
	v_mov_b32_e32 v78, v2
	v_mov_b32_e32 v79, v2
	v_mov_b32_e32 v80, v2
	v_mov_b32_e32 v81, v2
	v_mov_b32_e32 v62, v2
	v_mov_b32_e32 v63, v2
	v_mov_b32_e32 v64, v2
	v_mov_b32_e32 v65, v2
	v_mov_b32_e32 v70, v2
	v_mov_b32_e32 v71, v2
	v_mov_b32_e32 v72, v2
	v_mov_b32_e32 v73, v2
	v_mov_b32_e32 v86, v2
	v_mov_b32_e32 v87, v2
	v_mov_b32_e32 v88, v2
	v_mov_b32_e32 v89, v2
	v_mov_b32_e32 v94, v2
	v_mov_b32_e32 v95, v2
	v_mov_b32_e32 v96, v2
	v_mov_b32_e32 v97, v2
	v_mov_b32_e32 v98, v2
	v_mov_b32_e32 v99, v2
	v_mov_b32_e32 v100, v2
	v_mov_b32_e32 v101, v2
	v_mov_b32_e32 v106, v2
	v_mov_b32_e32 v107, v2
	v_mov_b32_e32 v108, v2
	v_mov_b32_e32 v109, v2
	v_mov_b32_e32 v82, v2
	v_mov_b32_e32 v83, v2
	v_mov_b32_e32 v84, v2
	v_mov_b32_e32 v85, v2
	v_mov_b32_e32 v90, v2
	v_mov_b32_e32 v91, v2
	v_mov_b32_e32 v92, v2
	v_mov_b32_e32 v93, v2
	v_mov_b32_e32 v102, v2
	v_mov_b32_e32 v103, v2
	v_mov_b32_e32 v104, v2
	v_mov_b32_e32 v105, v2
	v_mov_b32_e32 v110, v2
	v_mov_b32_e32 v111, v2
	v_mov_b32_e32 v112, v2
	v_mov_b32_e32 v113, v2
	v_mov_b32_e32 v114, v2
	v_mov_b32_e32 v115, v2
	v_mov_b32_e32 v116, v2
	v_mov_b32_e32 v117, v2
	v_mov_b32_e32 v118, v2
	v_mov_b32_e32 v119, v2
	v_mov_b32_e32 v120, v2
	v_mov_b32_e32 v121, v2
	v_mov_b32_e32 v122, v2
	v_mov_b32_e32 v123, v2
	v_mov_b32_e32 v124, v2
	v_mov_b32_e32 v125, v2
	v_mov_b32_e32 v126, v2
	v_mov_b32_e32 v127, v2
	v_mov_b32_e32 v128, v2
	v_mov_b32_e32 v129, v2
	s_add_u32 s4, s44, 0x100
	s_addc_u32 s5, s45, 0
	s_add_i32 s34, 0, 0x10000
	s_cmp_eq_u32 s31, 28
	s_cselect_b32 s43, s95, s5
	s_cselect_b32 s42, s94, s4
	s_cselect_b32 s7, s27, s30
	s_cselect_b32 s6, s28, s29
	s_add_i32 s35, 0, 0x14000
	v_add_u32_e32 v142, s34, v196
	v_add_u32_e32 v158, s35, v196
	ds_read_b128 v[130:133], v142
	ds_read_b128 v[134:137], v142 offset:1024
	ds_read_b128 v[138:141], v142 offset:2048
	ds_read_b128 v[142:145], v142 offset:3072
	ds_read_b128 v[146:149], v158
	ds_read_b128 v[150:153], v158 offset:1024
	ds_read_b128 v[154:157], v158 offset:2048
	ds_read_b128 v[158:161], v158 offset:3072
	v_lshl_add_u64 v[194:195], s[44:45], 0, v[186:187]
	s_add_i32 m0, s93, 0xc000
	ds_read_b128 v[162:165], v201
	ds_read_b128 v[166:169], v201 offset:1024
	ds_read_b128 v[170:173], v201 offset:2048
	ds_read_b128 v[174:177], v201 offset:3072
	ds_read_b128 v[190:193], v201 offset:4096
	ds_read_b128 v[202:205], v201 offset:5120
	ds_read_b128 v[206:209], v201 offset:6144
	ds_read_b128 v[210:213], v201 offset:7168
	global_load_lds_dwordx4 v[194:195], off
	v_lshl_add_u64 v[194:195], s[44:45], 0, v[188:189]
	s_add_i32 m0, s93, 0xe000
	s_nop 0
	global_load_lds_dwordx4 v[194:195], off
	s_waitcnt lgkmcnt(0)
	s_setprio 1
	s_barrier
; #define PG8_STAGE(bufoff, gbase, voff) do { _Pragma("unroll") for (int _i = 0; _i < 2; ++_i) \
;         __builtin_amdgcn_global_load_lds((const unsigned*)((const char*)(gbase) + (voff)[_i]), (LAS unsigned*)(lds + (bufoff) + ldsw + _i * 8192), 16, 0, 0); } while (0)
; #define PG8_LDA(dst, b, h) do { _Pragma("unroll") for (int m = 0; m < 4; ++m) _Pragma("unroll") for (int k = 0; k < 2; ++k) dst[m][k] = *(const LAS bf16x8*)(lds + PG8_SA(b, h) + aoff + m * 2048 + k * 1024); } while (0)
; #define PG8_MMA(ai, bj, At, Bt) do { __builtin_amdgcn_s_setprio(1); _Pragma("unroll") for (int m = 0; m < 4; ++m) _Pragma("unroll") for (int n = 0; n < 2; ++n) _Pragma("unroll") for (int k = 0; k < 2; ++k) \
;         acc[ai][bj][m][n] = __builtin_amdgcn_mfma_f32_16x16x32_bf16(Bt[n][k], At[m][k], acc[ai][bj][m][n], 0, 0, 0); __builtin_amdgcn_s_setprio(0); } while (0)
; #define PG8_WAIT_V(n) asm volatile("s_waitcnt vmcnt(" #n ")" ::: "memory")
; #define PG8_WAIT_L(n) asm volatile("s_waitcnt lgkmcnt(" #n ")" ::: "memory")
; #define PG8_BAR __builtin_amdgcn_s_barrier()
; #define PG8_SCHED __builtin_amdgcn_sched_barrier(0)
; template <class Epi, int AMODE>
; __device__ __forceinline__ void gemm_phase(LAS unsigned char* lds, const Gemm g, const StaticOrder& S, const Epi& E, int stagger_us, int tid_in) {
;     ...
;             PG8_WAIT_V(8); PG8_WAIT_L(0); PG8_BAR; PG8_MMA(0, 0, At, B0); PG8_MMA(0, 1, At, B1); PG8_BAR; PG8_SCHED;
;             PG8_LDA(At, 0, 1); PG8_STAGE(PG8_SB(0, 0), b2, voffB); PG8_STAGE(PG8_SB(0, 1), b2 + hstepB, voffB); PG8_STAGE(PG8_SA(0, 0), a2, voffA);
;             PG8_WAIT_V(8); PG8_WAIT_L(0); PG8_BAR; PG8_MMA(1, 0, At, B0); PG8_MMA(1, 1, At, B1); PG8_BAR; PG8_SCHED;
	v_mfma_f32_16x16x32_bf16 v[126:129], v[130:133], v[162:165], v[126:129]
	v_mfma_f32_16x16x32_bf16 v[122:125], v[138:141], v[162:165], v[122:125]
	v_mfma_f32_16x16x32_bf16 v[118:121], v[130:133], v[170:173], v[118:121]
	v_mfma_f32_16x16x32_bf16 v[114:117], v[138:141], v[170:173], v[114:117]
	v_mfma_f32_16x16x32_bf16 v[110:113], v[130:133], v[190:193], v[110:113]
	v_mfma_f32_16x16x32_bf16 v[102:105], v[138:141], v[190:193], v[102:105]
	v_mfma_f32_16x16x32_bf16 v[90:93], v[130:133], v[206:209], v[90:93]
	v_mfma_f32_16x16x32_bf16 v[82:85], v[138:141], v[206:209], v[82:85]
	v_mfma_f32_16x16x32_bf16 v[126:129], v[134:137], v[166:169], v[126:129]
	v_mfma_f32_16x16x32_bf16 v[122:125], v[142:145], v[166:169], v[122:125]
	v_mfma_f32_16x16x32_bf16 v[118:121], v[134:137], v[174:177], v[118:121]
	v_mfma_f32_16x16x32_bf16 v[114:117], v[142:145], v[174:177], v[114:117]
	v_mfma_f32_16x16x32_bf16 v[110:113], v[134:137], v[202:205], v[110:113]
	v_mfma_f32_16x16x32_bf16 v[102:105], v[142:145], v[202:205], v[102:105]
	v_mfma_f32_16x16x32_bf16 v[90:93], v[134:137], v[210:213], v[90:93]
	v_mfma_f32_16x16x32_bf16 v[82:85], v[142:145], v[210:213], v[82:85]
	v_mfma_f32_16x16x32_bf16 v[106:109], v[146:149], v[162:165], v[106:109]
	v_mfma_f32_16x16x32_bf16 v[98:101], v[154:157], v[162:165], v[98:101]
	v_mfma_f32_16x16x32_bf16 v[94:97], v[146:149], v[170:173], v[94:97]
	v_mfma_f32_16x16x32_bf16 v[86:89], v[154:157], v[170:173], v[86:89]
	v_mfma_f32_16x16x32_bf16 v[70:73], v[146:149], v[190:193], v[70:73]
	v_mfma_f32_16x16x32_bf16 v[62:65], v[154:157], v[190:193], v[62:65]
	v_mfma_f32_16x16x32_bf16 v[78:81], v[146:149], v[206:209], v[78:81]
	v_mfma_f32_16x16x32_bf16 v[66:69], v[154:157], v[206:209], v[66:69]
	v_mfma_f32_16x16x32_bf16 v[106:109], v[150:153], v[166:169], v[106:109]
	v_mfma_f32_16x16x32_bf16 v[98:101], v[158:161], v[166:169], v[98:101]
	v_mfma_f32_16x16x32_bf16 v[94:97], v[150:153], v[174:177], v[94:97]
	v_mfma_f32_16x16x32_bf16 v[86:89], v[158:161], v[174:177], v[86:89]
	v_mfma_f32_16x16x32_bf16 v[70:73], v[150:153], v[202:205], v[70:73]
	v_mfma_f32_16x16x32_bf16 v[62:65], v[158:161], v[202:205], v[62:65]
	v_mfma_f32_16x16x32_bf16 v[78:81], v[150:153], v[210:213], v[78:81]
	v_mfma_f32_16x16x32_bf16 v[66:69], v[158:161], v[210:213], v[66:69]
	s_barrier
	s_setprio 0
	s_add_i32 s34, s34, s91
	v_lshl_add_u64 v[194:195], s[6:7], 0, v[0:1]
	s_mov_b32 m0, s34
	ds_read_b128 v[162:165], v201 offset:16384
	ds_read_b128 v[166:169], v201 offset:17408
	ds_read_b128 v[170:173], v201 offset:18432
	ds_read_b128 v[174:177], v201 offset:19456
	ds_read_b128 v[190:193], v201 offset:20480
	ds_read_b128 v[202:205], v201 offset:21504
	ds_read_b128 v[206:209], v201 offset:22528
	ds_read_b128 v[210:213], v201 offset:23552
	global_load_lds_dwordx4 v[194:195], off
	s_add_i32 m0, s34, 0x2000
	s_add_u32 s44, s6, 0x80000
	v_lshl_add_u64 v[214:215], s[6:7], 0, v[182:183]
	s_addc_u32 s45, s7, 0
	s_add_i32 s34, s35, s91
	global_load_lds_dwordx4 v[214:215], off
	v_lshl_add_u64 v[216:217], s[44:45], 0, v[0:1]
	s_mov_b32 m0, s34
	v_lshl_add_u64 v[218:219], s[42:43], 0, v[180:181]
	global_load_lds_dwordx4 v[216:217], off
	v_lshl_add_u64 v[216:217], s[44:45], 0, v[182:183]
	s_add_i32 m0, s34, 0x2000
	s_nop 0
	global_load_lds_dwordx4 v[216:217], off
	v_lshl_add_u64 v[216:217], s[42:43], 0, v[178:179]
	s_mov_b32 m0, s93
	s_nop 0
	global_load_lds_dwordx4 v[216:217], off
	s_mov_b32 m0, s83
	s_nop 0
	global_load_lds_dwordx4 v[218:219], off
	s_waitcnt lgkmcnt(0)
	s_setprio 1
	s_barrier
	v_mfma_f32_16x16x32_bf16 v[54:57], v[130:133], v[162:165], v[54:57]
	v_mfma_f32_16x16x32_bf16 v[46:49], v[138:141], v[162:165], v[46:49]
	v_mfma_f32_16x16x32_bf16 v[38:41], v[130:133], v[170:173], v[38:41]
	v_mfma_f32_16x16x32_bf16 v[50:53], v[138:141], v[170:173], v[50:53]
	v_mfma_f32_16x16x32_bf16 v[18:21], v[130:133], v[190:193], v[18:21]
	v_mfma_f32_16x16x32_bf16 v[34:37], v[138:141], v[190:193], v[34:37]
	v_mfma_f32_16x16x32_bf16 v[22:25], v[130:133], v[206:209], v[22:25]
	v_mfma_f32_16x16x32_bf16 v[74:77], v[138:141], v[206:209], v[74:77]
	v_mfma_f32_16x16x32_bf16 v[54:57], v[134:137], v[166:169], v[54:57]
	v_mfma_f32_16x16x32_bf16 v[46:49], v[142:145], v[166:169], v[46:49]
	v_mfma_f32_16x16x32_bf16 v[38:41], v[134:137], v[174:177], v[38:41]
	v_mfma_f32_16x16x32_bf16 v[50:53], v[142:145], v[174:177], v[50:53]
	v_mfma_f32_16x16x32_bf16 v[18:21], v[134:137], v[202:205], v[18:21]
	v_mfma_f32_16x16x32_bf16 v[34:37], v[142:145], v[202:205], v[34:37]
	v_mfma_f32_16x16x32_bf16 v[22:25], v[134:137], v[210:213], v[22:25]
	v_mfma_f32_16x16x32_bf16 v[74:77], v[142:145], v[210:213], v[74:77]
	v_mfma_f32_16x16x32_bf16 v[58:61], v[146:149], v[162:165], v[58:61]
	v_mfma_f32_16x16x32_bf16 v[30:33], v[154:157], v[162:165], v[30:33]
	v_mfma_f32_16x16x32_bf16 v[42:45], v[146:149], v[170:173], v[42:45]
	v_mfma_f32_16x16x32_bf16 v[6:9], v[154:157], v[170:173], v[6:9]
	v_mfma_f32_16x16x32_bf16 v[26:29], v[146:149], v[190:193], v[26:29]
	v_mfma_f32_16x16x32_bf16 v[10:13], v[154:157], v[190:193], v[10:13]
	v_mfma_f32_16x16x32_bf16 v[14:17], v[146:149], v[206:209], v[14:17]
	v_mfma_f32_16x16x32_bf16 v[2:5], v[154:157], v[206:209], v[2:5]
	v_mfma_f32_16x16x32_bf16 v[58:61], v[150:153], v[166:169], v[58:61]
	v_mfma_f32_16x16x32_bf16 v[30:33], v[158:161], v[166:169], v[30:33]
	v_mfma_f32_16x16x32_bf16 v[42:45], v[150:153], v[174:177], v[42:45]
	v_mfma_f32_16x16x32_bf16 v[6:9], v[158:161], v[174:177], v[6:9]
	v_mfma_f32_16x16x32_bf16 v[26:29], v[150:153], v[202:205], v[26:29]
	v_mfma_f32_16x16x32_bf16 v[10:13], v[158:161], v[202:205], v[10:13]
	v_mfma_f32_16x16x32_bf16 v[14:17], v[150:153], v[210:213], v[14:17]
	v_mfma_f32_16x16x32_bf16 v[2:5], v[158:161], v[210:213], v[2:5]
	s_barrier
; #define PG8_STAGE(bufoff, gbase, voff) do { _Pragma("unroll") for (int _i = 0; _i < 2; ++_i) \
;         __builtin_amdgcn_global_load_lds((const unsigned*)((const char*)(gbase) + (voff)[_i]), (LAS unsigned*)(lds + (bufoff) + ldsw + _i * 8192), 16, 0, 0); } while (0)
; #define PG8_LDA(dst, b, h) do { _Pragma("unroll") for (int m = 0; m < 4; ++m) _Pragma("unroll") for (int k = 0; k < 2; ++k) dst[m][k] = *(const LAS bf16x8*)(lds + PG8_SA(b, h) + aoff + m * 2048 + k * 1024); } while (0)
; #define PG8_LDB(dst, b, h) do { _Pragma("unroll") for (int n = 0; n < 2; ++n) _Pragma("unroll") for (int k = 0; k < 2; ++k) dst[n][k] = *(const LAS bf16x8*)(lds + PG8_SB(b, h) + boff + n * 2048 + k * 1024); } while (0)
; #define PG8_MMA(ai, bj, At, Bt) do { __builtin_amdgcn_s_setprio(1); _Pragma("unroll") for (int m = 0; m < 4; ++m) _Pragma("unroll") for (int n = 0; n < 2; ++n) _Pragma("unroll") for (int k = 0; k < 2; ++k) \
;         acc[ai][bj][m][n] = __builtin_amdgcn_mfma_f32_16x16x32_bf16(Bt[n][k], At[m][k], acc[ai][bj][m][n], 0, 0, 0); __builtin_amdgcn_s_setprio(0); } while (0)
; #define PG8_WAIT_V(n) asm volatile("s_waitcnt vmcnt(" #n ")" ::: "memory")
; #define PG8_WAIT_L(n) asm volatile("s_waitcnt lgkmcnt(" #n ")" ::: "memory")
; #define PG8_BAR __builtin_amdgcn_s_barrier()
; #define PG8_SCHED __builtin_amdgcn_sched_barrier(0)
; template <class Epi, int AMODE>
; __device__ __forceinline__ void gemm_phase(LAS unsigned char* lds, const Gemm g, const StaticOrder& S, const Epi& E, int stagger_us, int tid_in) {
;     ...
;             PG8_WAIT_V(8); PG8_WAIT_L(0); PG8_BAR; PG8_MMA(1, 0, At, B0); PG8_MMA(1, 1, At, B1); PG8_BAR; PG8_SCHED;
;             PG8_LDB(B0, 1, 0); PG8_LDB(B1, 1, 1); PG8_SCHED; PG8_LDA(At, 1, 0); PG8_STAGE(PG8_SA(0, 1), a2 + hstepA, voffA);
;             PG8_WAIT_V(8); PG8_WAIT_L(0); PG8_BAR; PG8_MMA(0, 0, At, B0); PG8_MMA(0, 1, At, B1); PG8_BAR; PG8_SCHED;
;             PG8_LDA(At, 1, 1); PG8_STAGE(PG8_SB(1, 0), b3, voffB); PG8_STAGE(PG8_SB(1, 1), b3 + hstepB, voffB); PG8_STAGE(PG8_SA(1, 0), a3, voffA);
;             PG8_WAIT_V(8); PG8_WAIT_L(0); PG8_BAR; PG8_MMA(1, 0, At, B0); PG8_MMA(1, 1, At, B1); PG8_BAR; PG8_SCHED;
	s_setprio 0
	s_add_i32 s34, 0, 0x18000
	s_add_i32 s35, 0, 0x1c000
	v_add_u32_e32 v142, s34, v196
	v_add_u32_e32 v158, s35, v196
	ds_read_b128 v[130:133], v142
	ds_read_b128 v[134:137], v142 offset:1024
	ds_read_b128 v[138:141], v142 offset:2048
	ds_read_b128 v[142:145], v142 offset:3072
	ds_read_b128 v[146:149], v158
	ds_read_b128 v[150:153], v158 offset:1024
	ds_read_b128 v[154:157], v158 offset:2048
	ds_read_b128 v[158:161], v158 offset:3072
	s_add_u32 s42, s42, 0x4000
	s_addc_u32 s43, s43, 0
	s_mov_b32 m0, s79
	v_lshl_add_u64 v[220:221], s[42:43], 0, v[178:179]
	ds_read_b128 v[162:165], v201 offset:32768
	ds_read_b128 v[166:169], v201 offset:33792
	ds_read_b128 v[170:173], v201 offset:34816
	ds_read_b128 v[174:177], v201 offset:35840
	ds_read_b128 v[190:193], v201 offset:36864
	ds_read_b128 v[202:205], v201 offset:37888
	ds_read_b128 v[206:209], v201 offset:38912
	ds_read_b128 v[210:213], v201 offset:39936
	global_load_lds_dwordx4 v[220:221], off
	v_lshl_add_u64 v[220:221], s[42:43], 0, v[180:181]
	s_mov_b32 m0, s87
	s_nop 0
	global_load_lds_dwordx4 v[220:221], off
	s_waitcnt vmcnt(8)
	s_waitcnt lgkmcnt(0)
	s_setprio 1
	s_barrier
	v_mfma_f32_16x16x32_bf16 v[126:129], v[130:133], v[162:165], v[126:129]
	v_mfma_f32_16x16x32_bf16 v[122:125], v[138:141], v[162:165], v[122:125]
	v_mfma_f32_16x16x32_bf16 v[118:121], v[130:133], v[170:173], v[118:121]
	v_mfma_f32_16x16x32_bf16 v[114:117], v[138:141], v[170:173], v[114:117]
	v_mfma_f32_16x16x32_bf16 v[110:113], v[130:133], v[190:193], v[110:113]
	v_mfma_f32_16x16x32_bf16 v[102:105], v[138:141], v[190:193], v[102:105]
	v_mfma_f32_16x16x32_bf16 v[90:93], v[130:133], v[206:209], v[90:93]
	v_mfma_f32_16x16x32_bf16 v[82:85], v[138:141], v[206:209], v[82:85]
	v_mfma_f32_16x16x32_bf16 v[126:129], v[134:137], v[166:169], v[126:129]
	v_mfma_f32_16x16x32_bf16 v[122:125], v[142:145], v[166:169], v[122:125]
	v_mfma_f32_16x16x32_bf16 v[118:121], v[134:137], v[174:177], v[118:121]
	v_mfma_f32_16x16x32_bf16 v[114:117], v[142:145], v[174:177], v[114:117]
	v_mfma_f32_16x16x32_bf16 v[110:113], v[134:137], v[202:205], v[110:113]
	v_mfma_f32_16x16x32_bf16 v[102:105], v[142:145], v[202:205], v[102:105]
	v_mfma_f32_16x16x32_bf16 v[90:93], v[134:137], v[210:213], v[90:93]
	v_mfma_f32_16x16x32_bf16 v[82:85], v[142:145], v[210:213], v[82:85]
	v_mfma_f32_16x16x32_bf16 v[106:109], v[146:149], v[162:165], v[106:109]
	v_mfma_f32_16x16x32_bf16 v[98:101], v[154:157], v[162:165], v[98:101]
	v_mfma_f32_16x16x32_bf16 v[94:97], v[146:149], v[170:173], v[94:97]
	v_mfma_f32_16x16x32_bf16 v[86:89], v[154:157], v[170:173], v[86:89]
	v_mfma_f32_16x16x32_bf16 v[70:73], v[146:149], v[190:193], v[70:73]
	v_mfma_f32_16x16x32_bf16 v[62:65], v[154:157], v[190:193], v[62:65]
	v_mfma_f32_16x16x32_bf16 v[78:81], v[146:149], v[206:209], v[78:81]
	v_mfma_f32_16x16x32_bf16 v[66:69], v[154:157], v[206:209], v[66:69]
	v_mfma_f32_16x16x32_bf16 v[106:109], v[150:153], v[166:169], v[106:109]
	v_mfma_f32_16x16x32_bf16 v[98:101], v[158:161], v[166:169], v[98:101]
	v_mfma_f32_16x16x32_bf16 v[94:97], v[150:153], v[174:177], v[94:97]
	v_mfma_f32_16x16x32_bf16 v[86:89], v[158:161], v[174:177], v[86:89]
	v_mfma_f32_16x16x32_bf16 v[70:73], v[150:153], v[202:205], v[70:73]
	v_mfma_f32_16x16x32_bf16 v[62:65], v[158:161], v[202:205], v[62:65]
	v_mfma_f32_16x16x32_bf16 v[78:81], v[150:153], v[210:213], v[78:81]
	v_mfma_f32_16x16x32_bf16 v[66:69], v[158:161], v[210:213], v[66:69]
	s_barrier
	s_setprio 0
	s_add_i32 s34, s34, s91
	v_lshl_add_u64 v[194:195], v[194:195], 0, s[74:75]
	s_mov_b32 m0, s34
	ds_read_b128 v[162:165], v201 offset:49152
	ds_read_b128 v[166:169], v201 offset:50176
	ds_read_b128 v[170:173], v201 offset:51200
	ds_read_b128 v[174:177], v201 offset:52224
	ds_read_b128 v[190:193], v201 offset:53248
	ds_read_b128 v[202:205], v201 offset:54272
	ds_read_b128 v[206:209], v201 offset:55296
	ds_read_b128 v[210:213], v201 offset:56320
	global_load_lds_dwordx4 v[194:195], off
	s_add_i32 m0, s34, 0x2000
	s_add_u32 s6, s6, 0x80080
	v_lshl_add_u64 v[194:195], v[214:215], 0, s[74:75]
	s_addc_u32 s7, s7, 0
	s_add_i32 s34, s35, s91
	global_load_lds_dwordx4 v[194:195], off
	v_lshl_add_u64 v[194:195], s[6:7], 0, v[0:1]
	s_mov_b32 m0, s34
	s_nop 0
	global_load_lds_dwordx4 v[194:195], off
	v_lshl_add_u64 v[194:195], s[6:7], 0, v[182:183]
	s_add_i32 m0, s34, 0x2000
	s_nop 0
	global_load_lds_dwordx4 v[194:195], off
	v_lshl_add_u64 v[194:195], v[216:217], 0, s[74:75]
	s_mov_b32 m0, s67
	s_nop 0
	global_load_lds_dwordx4 v[194:195], off
	v_lshl_add_u64 v[194:195], v[218:219], 0, s[74:75]
	s_mov_b32 m0, s85
	s_nop 0
	global_load_lds_dwordx4 v[194:195], off
	s_waitcnt vmcnt(8)
	s_waitcnt lgkmcnt(0)
	s_setprio 1
	s_barrier
	v_mfma_f32_16x16x32_bf16 v[54:57], v[130:133], v[162:165], v[54:57]
	v_mfma_f32_16x16x32_bf16 v[46:49], v[138:141], v[162:165], v[46:49]
	v_mfma_f32_16x16x32_bf16 v[38:41], v[130:133], v[170:173], v[38:41]
	v_mfma_f32_16x16x32_bf16 v[50:53], v[138:141], v[170:173], v[50:53]
	v_mfma_f32_16x16x32_bf16 v[18:21], v[130:133], v[190:193], v[18:21]
	v_mfma_f32_16x16x32_bf16 v[34:37], v[138:141], v[190:193], v[34:37]
	v_mfma_f32_16x16x32_bf16 v[22:25], v[130:133], v[206:209], v[22:25]
	v_mfma_f32_16x16x32_bf16 v[74:77], v[138:141], v[206:209], v[74:77]
	v_mfma_f32_16x16x32_bf16 v[54:57], v[134:137], v[166:169], v[54:57]
	v_mfma_f32_16x16x32_bf16 v[46:49], v[142:145], v[166:169], v[46:49]
	v_mfma_f32_16x16x32_bf16 v[38:41], v[134:137], v[174:177], v[38:41]
	v_mfma_f32_16x16x32_bf16 v[50:53], v[142:145], v[174:177], v[50:53]
	v_mfma_f32_16x16x32_bf16 v[18:21], v[134:137], v[202:205], v[18:21]
	v_mfma_f32_16x16x32_bf16 v[34:37], v[142:145], v[202:205], v[34:37]
	v_mfma_f32_16x16x32_bf16 v[22:25], v[134:137], v[210:213], v[22:25]
	v_mfma_f32_16x16x32_bf16 v[74:77], v[142:145], v[210:213], v[74:77]
	v_mfma_f32_16x16x32_bf16 v[58:61], v[146:149], v[162:165], v[58:61]
	v_mfma_f32_16x16x32_bf16 v[30:33], v[154:157], v[162:165], v[30:33]
	v_mfma_f32_16x16x32_bf16 v[42:45], v[146:149], v[170:173], v[42:45]
	v_mfma_f32_16x16x32_bf16 v[6:9], v[154:157], v[170:173], v[6:9]
	v_mfma_f32_16x16x32_bf16 v[26:29], v[146:149], v[190:193], v[26:29]
	v_mfma_f32_16x16x32_bf16 v[10:13], v[154:157], v[190:193], v[10:13]
	v_mfma_f32_16x16x32_bf16 v[14:17], v[146:149], v[206:209], v[14:17]
	v_mfma_f32_16x16x32_bf16 v[2:5], v[154:157], v[206:209], v[2:5]
	v_mfma_f32_16x16x32_bf16 v[58:61], v[150:153], v[166:169], v[58:61]
	v_mfma_f32_16x16x32_bf16 v[30:33], v[158:161], v[166:169], v[30:33]
	v_mfma_f32_16x16x32_bf16 v[42:45], v[150:153], v[174:177], v[42:45]
	v_mfma_f32_16x16x32_bf16 v[6:9], v[158:161], v[174:177], v[6:9]
	v_mfma_f32_16x16x32_bf16 v[26:29], v[150:153], v[202:205], v[26:29]
	v_mfma_f32_16x16x32_bf16 v[10:13], v[158:161], v[202:205], v[10:13]
	v_mfma_f32_16x16x32_bf16 v[14:17], v[150:153], v[210:213], v[14:17]
	v_mfma_f32_16x16x32_bf16 v[2:5], v[158:161], v[210:213], v[2:5]
	s_barrier
	s_setprio 0
	s_add_i32 s31, s31, 2
	s_add_u32 s29, s29, 0x100
	s_addc_u32 s30, s30, 0
	s_cmp_gt_u32 s31, 29
	s_mov_b64 s[44:45], s[4:5]
; #define PG8_STAGE(bufoff, gbase, voff) do { _Pragma("unroll") for (int _i = 0; _i < 2; ++_i) \
;         __builtin_amdgcn_global_load_lds((const unsigned*)((const char*)(gbase) + (voff)[_i]), (LAS unsigned*)(lds + (bufoff) + ldsw + _i * 8192), 16, 0, 0); } while (0)
; #define PG8_LDA(dst, b, h) do { _Pragma("unroll") for (int m = 0; m < 4; ++m) _Pragma("unroll") for (int k = 0; k < 2; ++k) dst[m][k] = *(const LAS bf16x8*)(lds + PG8_SA(b, h) + aoff + m * 2048 + k * 1024); } while (0)
; #define PG8_LDB(dst, b, h) do { _Pragma("unroll") for (int n = 0; n < 2; ++n) _Pragma("unroll") for (int k = 0; k < 2; ++k) dst[n][k] = *(const LAS bf16x8*)(lds + PG8_SB(b, h) + boff + n * 2048 + k * 1024); } while (0)
; #define PG8_MMA(ai, bj, At, Bt) do { __builtin_amdgcn_s_setprio(1); _Pragma("unroll") for (int m = 0; m < 4; ++m) _Pragma("unroll") for (int n = 0; n < 2; ++n) _Pragma("unroll") for (int k = 0; k < 2; ++k) \
;         acc[ai][bj][m][n] = __builtin_amdgcn_mfma_f32_16x16x32_bf16(Bt[n][k], At[m][k], acc[ai][bj][m][n], 0, 0, 0); __builtin_amdgcn_s_setprio(0); } while (0)
; #define PG8_BAR __builtin_amdgcn_s_barrier()
; template <class Epi, int AMODE>
; __device__ __forceinline__ void gemm_phase(LAS unsigned char* lds, const Gemm g, const StaticOrder& S, const Epi& E, int stagger_us, int tid_in) {
;     ...
;         const bool has_next = S.next(ui + 1, nxt);
;         const char* nA = has_next ? Abase + (size_t)nxt.pm * tstepA : cA; const char* nB = has_next ? (const char*)g.Bt + (size_t)nxt.pn * tstepB : cB;
;         for (int t = 0; t < nt; t += 2) {
;             const bool last = (t == nt - 2);
;             const char* a1 = cA + (size_t)(t + 1) * kstep;
;             const char* a2 = last ? nA : cA + (size_t)(t + 2) * kstep; const char* b2 = last ? nB : cB + (size_t)(t + 2) * kstep;
;             const char* a3 = a2 + kstep; const char* b3 = b2 + kstep;
;             PG8_LDB(B0, 0, 0); PG8_LDB(B1, 0, 1); PG8_SCHED; PG8_LDA(At, 0, 0); PG8_STAGE(PG8_SA(1, 1), a1 + hstepA, voffA);
;             PG8_WAIT_V(8); PG8_WAIT_L(0); PG8_BAR; PG8_MMA(0, 0, At, B0); PG8_MMA(0, 1, At, B1); PG8_BAR; PG8_SCHED;
;             PG8_LDA(At, 0, 1); PG8_STAGE(PG8_SB(0, 0), b2, voffB); PG8_STAGE(PG8_SB(0, 1), b2 + hstepB, voffB); PG8_STAGE(PG8_SA(0, 0), a2, voffA);
;             PG8_WAIT_V(8); PG8_WAIT_L(0); PG8_BAR; PG8_MMA(1, 0, At, B0); PG8_MMA(1, 1, At, B1); PG8_BAR; PG8_SCHED;
.LBB0_1299:
	s_add_u32 s4, s44, 0x100
	s_addc_u32 s5, s45, 0
	s_add_i32 s34, 0, 0x10000
	s_cmp_eq_u32 s31, 28
	s_cselect_b32 s43, s95, s5
	s_cselect_b32 s42, s94, s4
	s_cselect_b32 s7, s27, s30
	s_cselect_b32 s6, s28, s29
	s_add_i32 s35, 0, 0x14000
	v_add_u32_e32 v142, s34, v196
	v_add_u32_e32 v158, s35, v196
	ds_read_b128 v[130:133], v142
	ds_read_b128 v[134:137], v142 offset:1024
	ds_read_b128 v[138:141], v142 offset:2048
	ds_read_b128 v[142:145], v142 offset:3072
	ds_read_b128 v[146:149], v158
	ds_read_b128 v[150:153], v158 offset:1024
	ds_read_b128 v[154:157], v158 offset:2048
	ds_read_b128 v[158:161], v158 offset:3072
	v_lshl_add_u64 v[194:195], s[44:45], 0, v[186:187]
	s_add_i32 m0, s93, 0xc000
	ds_read_b128 v[162:165], v201
	ds_read_b128 v[166:169], v201 offset:1024
	ds_read_b128 v[170:173], v201 offset:2048
	ds_read_b128 v[174:177], v201 offset:3072
	ds_read_b128 v[190:193], v201 offset:4096
	ds_read_b128 v[202:205], v201 offset:5120
	ds_read_b128 v[206:209], v201 offset:6144
	ds_read_b128 v[210:213], v201 offset:7168
	global_load_lds_dwordx4 v[194:195], off
	v_lshl_add_u64 v[194:195], s[44:45], 0, v[188:189]
	s_add_i32 m0, s93, 0xe000
	s_nop 0
	global_load_lds_dwordx4 v[194:195], off
	s_waitcnt vmcnt(8)
	s_waitcnt lgkmcnt(0)
	s_setprio 1
	s_barrier
	v_mfma_f32_16x16x32_bf16 v[126:129], v[130:133], v[162:165], v[126:129]
	v_mfma_f32_16x16x32_bf16 v[122:125], v[138:141], v[162:165], v[122:125]
	v_mfma_f32_16x16x32_bf16 v[118:121], v[130:133], v[170:173], v[118:121]
	v_mfma_f32_16x16x32_bf16 v[114:117], v[138:141], v[170:173], v[114:117]
	v_mfma_f32_16x16x32_bf16 v[110:113], v[130:133], v[190:193], v[110:113]
	v_mfma_f32_16x16x32_bf16 v[102:105], v[138:141], v[190:193], v[102:105]
	v_mfma_f32_16x16x32_bf16 v[90:93], v[130:133], v[206:209], v[90:93]
	v_mfma_f32_16x16x32_bf16 v[82:85], v[138:141], v[206:209], v[82:85]
	v_mfma_f32_16x16x32_bf16 v[126:129], v[134:137], v[166:169], v[126:129]
	v_mfma_f32_16x16x32_bf16 v[122:125], v[142:145], v[166:169], v[122:125]
	v_mfma_f32_16x16x32_bf16 v[118:121], v[134:137], v[174:177], v[118:121]
	v_mfma_f32_16x16x32_bf16 v[114:117], v[142:145], v[174:177], v[114:117]
	v_mfma_f32_16x16x32_bf16 v[110:113], v[134:137], v[202:205], v[110:113]
	v_mfma_f32_16x16x32_bf16 v[102:105], v[142:145], v[202:205], v[102:105]
	v_mfma_f32_16x16x32_bf16 v[90:93], v[134:137], v[210:213], v[90:93]
	v_mfma_f32_16x16x32_bf16 v[82:85], v[142:145], v[210:213], v[82:85]
	v_mfma_f32_16x16x32_bf16 v[106:109], v[146:149], v[162:165], v[106:109]
	v_mfma_f32_16x16x32_bf16 v[98:101], v[154:157], v[162:165], v[98:101]
	v_mfma_f32_16x16x32_bf16 v[94:97], v[146:149], v[170:173], v[94:97]
	v_mfma_f32_16x16x32_bf16 v[86:89], v[154:157], v[170:173], v[86:89]
	v_mfma_f32_16x16x32_bf16 v[70:73], v[146:149], v[190:193], v[70:73]
	v_mfma_f32_16x16x32_bf16 v[62:65], v[154:157], v[190:193], v[62:65]
	v_mfma_f32_16x16x32_bf16 v[78:81], v[146:149], v[206:209], v[78:81]
	v_mfma_f32_16x16x32_bf16 v[66:69], v[154:157], v[206:209], v[66:69]
	v_mfma_f32_16x16x32_bf16 v[106:109], v[150:153], v[166:169], v[106:109]
	v_mfma_f32_16x16x32_bf16 v[98:101], v[158:161], v[166:169], v[98:101]
	v_mfma_f32_16x16x32_bf16 v[94:97], v[150:153], v[174:177], v[94:97]
	v_mfma_f32_16x16x32_bf16 v[86:89], v[158:161], v[174:177], v[86:89]
	v_mfma_f32_16x16x32_bf16 v[70:73], v[150:153], v[202:205], v[70:73]
	v_mfma_f32_16x16x32_bf16 v[62:65], v[158:161], v[202:205], v[62:65]
	v_mfma_f32_16x16x32_bf16 v[78:81], v[150:153], v[210:213], v[78:81]
	v_mfma_f32_16x16x32_bf16 v[66:69], v[158:161], v[210:213], v[66:69]
	s_barrier
	s_setprio 0
	s_add_i32 s34, s34, s91
	v_lshl_add_u64 v[194:195], s[6:7], 0, v[0:1]
	s_mov_b32 m0, s34
	ds_read_b128 v[162:165], v201 offset:16384
	ds_read_b128 v[166:169], v201 offset:17408
	ds_read_b128 v[170:173], v201 offset:18432
	ds_read_b128 v[174:177], v201 offset:19456
	ds_read_b128 v[190:193], v201 offset:20480
	ds_read_b128 v[202:205], v201 offset:21504
	ds_read_b128 v[206:209], v201 offset:22528
	ds_read_b128 v[210:213], v201 offset:23552
	global_load_lds_dwordx4 v[194:195], off
	s_add_i32 m0, s34, 0x2000
	s_add_u32 s44, s6, 0x80000
	v_lshl_add_u64 v[214:215], s[6:7], 0, v[182:183]
	s_addc_u32 s45, s7, 0
	s_add_i32 s34, s35, s91
	global_load_lds_dwordx4 v[214:215], off
	v_lshl_add_u64 v[216:217], s[44:45], 0, v[0:1]
	s_mov_b32 m0, s34
	v_lshl_add_u64 v[218:219], s[42:43], 0, v[180:181]
	global_load_lds_dwordx4 v[216:217], off
	v_lshl_add_u64 v[216:217], s[44:45], 0, v[182:183]
	s_add_i32 m0, s34, 0x2000
	s_nop 0
	global_load_lds_dwordx4 v[216:217], off
	v_lshl_add_u64 v[216:217], s[42:43], 0, v[178:179]
	s_mov_b32 m0, s93
	s_nop 0
	global_load_lds_dwordx4 v[216:217], off
	s_mov_b32 m0, s83
	s_nop 0
	global_load_lds_dwordx4 v[218:219], off
	s_waitcnt vmcnt(8)
	s_waitcnt lgkmcnt(0)
	s_setprio 1
	s_barrier
; #define PG8_STAGE(bufoff, gbase, voff) do { _Pragma("unroll") for (int _i = 0; _i < 2; ++_i) \
;         __builtin_amdgcn_global_load_lds((const unsigned*)((const char*)(gbase) + (voff)[_i]), (LAS unsigned*)(lds + (bufoff) + ldsw + _i * 8192), 16, 0, 0); } while (0)
; #define PG8_LDA(dst, b, h) do { _Pragma("unroll") for (int m = 0; m < 4; ++m) _Pragma("unroll") for (int k = 0; k < 2; ++k) dst[m][k] = *(const LAS bf16x8*)(lds + PG8_SA(b, h) + aoff + m * 2048 + k * 1024); } while (0)
; #define PG8_LDB(dst, b, h) do { _Pragma("unroll") for (int n = 0; n < 2; ++n) _Pragma("unroll") for (int k = 0; k < 2; ++k) dst[n][k] = *(const LAS bf16x8*)(lds + PG8_SB(b, h) + boff + n * 2048 + k * 1024); } while (0)
; #define PG8_MMA(ai, bj, At, Bt) do { __builtin_amdgcn_s_setprio(1); _Pragma("unroll") for (int m = 0; m < 4; ++m) _Pragma("unroll") for (int n = 0; n < 2; ++n) _Pragma("unroll") for (int k = 0; k < 2; ++k) \
;         acc[ai][bj][m][n] = __builtin_amdgcn_mfma_f32_16x16x32_bf16(Bt[n][k], At[m][k], acc[ai][bj][m][n], 0, 0, 0); __builtin_amdgcn_s_setprio(0); } while (0)
; #define PG8_WAIT_V(n) asm volatile("s_waitcnt vmcnt(" #n ")" ::: "memory")
; #define PG8_WAIT_L(n) asm volatile("s_waitcnt lgkmcnt(" #n ")" ::: "memory")
; #define PG8_BAR __builtin_amdgcn_s_barrier()
; #define PG8_SCHED __builtin_amdgcn_sched_barrier(0)
; template <class Epi, int AMODE>
; __device__ __forceinline__ void gemm_phase(LAS unsigned char* lds, const Gemm g, const StaticOrder& S, const Epi& E, int stagger_us, int tid_in) {
;     ...
;             PG8_WAIT_V(8); PG8_WAIT_L(0); PG8_BAR; PG8_MMA(1, 0, At, B0); PG8_MMA(1, 1, At, B1); PG8_BAR; PG8_SCHED;
;             PG8_LDB(B0, 1, 0); PG8_LDB(B1, 1, 1); PG8_SCHED; PG8_LDA(At, 1, 0); PG8_STAGE(PG8_SA(0, 1), a2 + hstepA, voffA);
;             PG8_WAIT_V(8); PG8_WAIT_L(0); PG8_BAR; PG8_MMA(0, 0, At, B0); PG8_MMA(0, 1, At, B1); PG8_BAR; PG8_SCHED;
	v_mfma_f32_16x16x32_bf16 v[54:57], v[130:133], v[162:165], v[54:57]
	v_mfma_f32_16x16x32_bf16 v[46:49], v[138:141], v[162:165], v[46:49]
	v_mfma_f32_16x16x32_bf16 v[38:41], v[130:133], v[170:173], v[38:41]
	v_mfma_f32_16x16x32_bf16 v[50:53], v[138:141], v[170:173], v[50:53]
	v_mfma_f32_16x16x32_bf16 v[18:21], v[130:133], v[190:193], v[18:21]
	v_mfma_f32_16x16x32_bf16 v[34:37], v[138:141], v[190:193], v[34:37]
	v_mfma_f32_16x16x32_bf16 v[22:25], v[130:133], v[206:209], v[22:25]
	v_mfma_f32_16x16x32_bf16 v[74:77], v[138:141], v[206:209], v[74:77]
	v_mfma_f32_16x16x32_bf16 v[54:57], v[134:137], v[166:169], v[54:57]
	v_mfma_f32_16x16x32_bf16 v[46:49], v[142:145], v[166:169], v[46:49]
	v_mfma_f32_16x16x32_bf16 v[38:41], v[134:137], v[174:177], v[38:41]
	v_mfma_f32_16x16x32_bf16 v[50:53], v[142:145], v[174:177], v[50:53]
	v_mfma_f32_16x16x32_bf16 v[18:21], v[134:137], v[202:205], v[18:21]
	v_mfma_f32_16x16x32_bf16 v[34:37], v[142:145], v[202:205], v[34:37]
	v_mfma_f32_16x16x32_bf16 v[22:25], v[134:137], v[210:213], v[22:25]
	v_mfma_f32_16x16x32_bf16 v[74:77], v[142:145], v[210:213], v[74:77]
	v_mfma_f32_16x16x32_bf16 v[58:61], v[146:149], v[162:165], v[58:61]
	v_mfma_f32_16x16x32_bf16 v[30:33], v[154:157], v[162:165], v[30:33]
	v_mfma_f32_16x16x32_bf16 v[42:45], v[146:149], v[170:173], v[42:45]
	v_mfma_f32_16x16x32_bf16 v[6:9], v[154:157], v[170:173], v[6:9]
	v_mfma_f32_16x16x32_bf16 v[26:29], v[146:149], v[190:193], v[26:29]
	v_mfma_f32_16x16x32_bf16 v[10:13], v[154:157], v[190:193], v[10:13]
	v_mfma_f32_16x16x32_bf16 v[14:17], v[146:149], v[206:209], v[14:17]
	v_mfma_f32_16x16x32_bf16 v[2:5], v[154:157], v[206:209], v[2:5]
	v_mfma_f32_16x16x32_bf16 v[58:61], v[150:153], v[166:169], v[58:61]
	v_mfma_f32_16x16x32_bf16 v[30:33], v[158:161], v[166:169], v[30:33]
	v_mfma_f32_16x16x32_bf16 v[42:45], v[150:153], v[174:177], v[42:45]
	v_mfma_f32_16x16x32_bf16 v[6:9], v[158:161], v[174:177], v[6:9]
	v_mfma_f32_16x16x32_bf16 v[26:29], v[150:153], v[202:205], v[26:29]
	v_mfma_f32_16x16x32_bf16 v[10:13], v[158:161], v[202:205], v[10:13]
	v_mfma_f32_16x16x32_bf16 v[14:17], v[150:153], v[210:213], v[14:17]
	v_mfma_f32_16x16x32_bf16 v[2:5], v[158:161], v[210:213], v[2:5]
	s_barrier
	s_setprio 0
	s_add_i32 s34, 0, 0x18000
	s_add_i32 s35, 0, 0x1c000
	v_add_u32_e32 v142, s34, v196
	v_add_u32_e32 v158, s35, v196
	ds_read_b128 v[130:133], v142
	ds_read_b128 v[134:137], v142 offset:1024
	ds_read_b128 v[138:141], v142 offset:2048
	ds_read_b128 v[142:145], v142 offset:3072
	ds_read_b128 v[146:149], v158
	ds_read_b128 v[150:153], v158 offset:1024
	ds_read_b128 v[154:157], v158 offset:2048
	ds_read_b128 v[158:161], v158 offset:3072
	s_add_u32 s42, s42, 0x4000
	s_addc_u32 s43, s43, 0
	s_mov_b32 m0, s79
	v_lshl_add_u64 v[220:221], s[42:43], 0, v[178:179]
	ds_read_b128 v[162:165], v201 offset:32768
	ds_read_b128 v[166:169], v201 offset:33792
	ds_read_b128 v[170:173], v201 offset:34816
	ds_read_b128 v[174:177], v201 offset:35840
	ds_read_b128 v[190:193], v201 offset:36864
	ds_read_b128 v[202:205], v201 offset:37888
	ds_read_b128 v[206:209], v201 offset:38912
	ds_read_b128 v[210:213], v201 offset:39936
	global_load_lds_dwordx4 v[220:221], off
	v_lshl_add_u64 v[220:221], s[42:43], 0, v[180:181]
	s_mov_b32 m0, s87
	s_nop 0
	global_load_lds_dwordx4 v[220:221], off
	s_waitcnt vmcnt(8)
	s_waitcnt lgkmcnt(0)
	s_setprio 1
	s_barrier
	v_mfma_f32_16x16x32_bf16 v[126:129], v[130:133], v[162:165], v[126:129]
	v_mfma_f32_16x16x32_bf16 v[122:125], v[138:141], v[162:165], v[122:125]
	v_mfma_f32_16x16x32_bf16 v[118:121], v[130:133], v[170:173], v[118:121]
	v_mfma_f32_16x16x32_bf16 v[114:117], v[138:141], v[170:173], v[114:117]
	v_mfma_f32_16x16x32_bf16 v[110:113], v[130:133], v[190:193], v[110:113]
	v_mfma_f32_16x16x32_bf16 v[102:105], v[138:141], v[190:193], v[102:105]
	v_mfma_f32_16x16x32_bf16 v[90:93], v[130:133], v[206:209], v[90:93]
	v_mfma_f32_16x16x32_bf16 v[82:85], v[138:141], v[206:209], v[82:85]
	v_mfma_f32_16x16x32_bf16 v[126:129], v[134:137], v[166:169], v[126:129]
	v_mfma_f32_16x16x32_bf16 v[122:125], v[142:145], v[166:169], v[122:125]
	v_mfma_f32_16x16x32_bf16 v[118:121], v[134:137], v[174:177], v[118:121]
	v_mfma_f32_16x16x32_bf16 v[114:117], v[142:145], v[174:177], v[114:117]
	v_mfma_f32_16x16x32_bf16 v[110:113], v[134:137], v[202:205], v[110:113]
	v_mfma_f32_16x16x32_bf16 v[102:105], v[142:145], v[202:205], v[102:105]
	v_mfma_f32_16x16x32_bf16 v[90:93], v[134:137], v[210:213], v[90:93]
	v_mfma_f32_16x16x32_bf16 v[82:85], v[142:145], v[210:213], v[82:85]
	v_mfma_f32_16x16x32_bf16 v[106:109], v[146:149], v[162:165], v[106:109]
	v_mfma_f32_16x16x32_bf16 v[98:101], v[154:157], v[162:165], v[98:101]
	v_mfma_f32_16x16x32_bf16 v[94:97], v[146:149], v[170:173], v[94:97]
	v_mfma_f32_16x16x32_bf16 v[86:89], v[154:157], v[170:173], v[86:89]
	v_mfma_f32_16x16x32_bf16 v[70:73], v[146:149], v[190:193], v[70:73]
	v_mfma_f32_16x16x32_bf16 v[62:65], v[154:157], v[190:193], v[62:65]
	v_mfma_f32_16x16x32_bf16 v[78:81], v[146:149], v[206:209], v[78:81]
	v_mfma_f32_16x16x32_bf16 v[66:69], v[154:157], v[206:209], v[66:69]
	v_mfma_f32_16x16x32_bf16 v[106:109], v[150:153], v[166:169], v[106:109]
	v_mfma_f32_16x16x32_bf16 v[98:101], v[158:161], v[166:169], v[98:101]
	v_mfma_f32_16x16x32_bf16 v[94:97], v[150:153], v[174:177], v[94:97]
	v_mfma_f32_16x16x32_bf16 v[86:89], v[158:161], v[174:177], v[86:89]
	v_mfma_f32_16x16x32_bf16 v[70:73], v[150:153], v[202:205], v[70:73]
	v_mfma_f32_16x16x32_bf16 v[62:65], v[158:161], v[202:205], v[62:65]
	v_mfma_f32_16x16x32_bf16 v[78:81], v[150:153], v[210:213], v[78:81]
	v_mfma_f32_16x16x32_bf16 v[66:69], v[158:161], v[210:213], v[66:69]
	s_barrier
; #define PG8_STAGE(bufoff, gbase, voff) do { _Pragma("unroll") for (int _i = 0; _i < 2; ++_i) \
;         __builtin_amdgcn_global_load_lds((const unsigned*)((const char*)(gbase) + (voff)[_i]), (LAS unsigned*)(lds + (bufoff) + ldsw + _i * 8192), 16, 0, 0); } while (0)
; #define PG8_LDA(dst, b, h) do { _Pragma("unroll") for (int m = 0; m < 4; ++m) _Pragma("unroll") for (int k = 0; k < 2; ++k) dst[m][k] = *(const LAS bf16x8*)(lds + PG8_SA(b, h) + aoff + m * 2048 + k * 1024); } while (0)
; #define PG8_MMA(ai, bj, At, Bt) do { __builtin_amdgcn_s_setprio(1); _Pragma("unroll") for (int m = 0; m < 4; ++m) _Pragma("unroll") for (int n = 0; n < 2; ++n) _Pragma("unroll") for (int k = 0; k < 2; ++k) \
;         acc[ai][bj][m][n] = __builtin_amdgcn_mfma_f32_16x16x32_bf16(Bt[n][k], At[m][k], acc[ai][bj][m][n], 0, 0, 0); __builtin_amdgcn_s_setprio(0); } while (0)
; #define PG8_WAIT_V(n) asm volatile("s_waitcnt vmcnt(" #n ")" ::: "memory")
; #define PG8_WAIT_L(n) asm volatile("s_waitcnt lgkmcnt(" #n ")" ::: "memory")
; #define PG8_BAR __builtin_amdgcn_s_barrier()
; #define PG8_SCHED __builtin_amdgcn_sched_barrier(0)
; template <class Epi, int AMODE>
; __device__ __forceinline__ void gemm_phase(LAS unsigned char* lds, const Gemm g, const StaticOrder& S, const Epi& E, int stagger_us, int tid_in) {
;     ...
;             PG8_LDA(At, 1, 1); PG8_STAGE(PG8_SB(1, 0), b3, voffB); PG8_STAGE(PG8_SB(1, 1), b3 + hstepB, voffB); PG8_STAGE(PG8_SA(1, 0), a3, voffA);
;             PG8_WAIT_V(8); PG8_WAIT_L(0); PG8_BAR; PG8_MMA(1, 0, At, B0); PG8_MMA(1, 1, At, B1); PG8_BAR; PG8_SCHED;
;         }
;         if (wr == 0) PG8_BAR;
	s_setprio 0
	s_add_i32 s34, s34, s91
	v_lshl_add_u64 v[194:195], v[194:195], 0, s[74:75]
	s_mov_b32 m0, s34
	ds_read_b128 v[162:165], v201 offset:49152
	ds_read_b128 v[166:169], v201 offset:50176
	ds_read_b128 v[170:173], v201 offset:51200
	ds_read_b128 v[174:177], v201 offset:52224
	ds_read_b128 v[190:193], v201 offset:53248
	ds_read_b128 v[202:205], v201 offset:54272
	ds_read_b128 v[206:209], v201 offset:55296
	ds_read_b128 v[210:213], v201 offset:56320
	global_load_lds_dwordx4 v[194:195], off
	s_add_i32 m0, s34, 0x2000
	s_add_u32 s6, s6, 0x80080
	v_lshl_add_u64 v[194:195], v[214:215], 0, s[74:75]
	s_addc_u32 s7, s7, 0
	s_add_i32 s34, s35, s91
	global_load_lds_dwordx4 v[194:195], off
	v_lshl_add_u64 v[194:195], s[6:7], 0, v[0:1]
	s_mov_b32 m0, s34
	s_nop 0
	global_load_lds_dwordx4 v[194:195], off
	v_lshl_add_u64 v[194:195], s[6:7], 0, v[182:183]
	s_add_i32 m0, s34, 0x2000
	s_nop 0
	global_load_lds_dwordx4 v[194:195], off
	v_lshl_add_u64 v[194:195], v[216:217], 0, s[74:75]
	s_mov_b32 m0, s67
	s_nop 0
	global_load_lds_dwordx4 v[194:195], off
	v_lshl_add_u64 v[194:195], v[218:219], 0, s[74:75]
	s_mov_b32 m0, s85
	s_nop 0
	global_load_lds_dwordx4 v[194:195], off
	s_waitcnt vmcnt(8)
	s_waitcnt lgkmcnt(0)
	s_setprio 1
	s_barrier
	v_mfma_f32_16x16x32_bf16 v[54:57], v[130:133], v[162:165], v[54:57]
	v_mfma_f32_16x16x32_bf16 v[46:49], v[138:141], v[162:165], v[46:49]
	v_mfma_f32_16x16x32_bf16 v[38:41], v[130:133], v[170:173], v[38:41]
	v_mfma_f32_16x16x32_bf16 v[50:53], v[138:141], v[170:173], v[50:53]
	v_mfma_f32_16x16x32_bf16 v[18:21], v[130:133], v[190:193], v[18:21]
	v_mfma_f32_16x16x32_bf16 v[34:37], v[138:141], v[190:193], v[34:37]
	v_mfma_f32_16x16x32_bf16 v[22:25], v[130:133], v[206:209], v[22:25]
	v_mfma_f32_16x16x32_bf16 v[74:77], v[138:141], v[206:209], v[74:77]
	v_mfma_f32_16x16x32_bf16 v[54:57], v[134:137], v[166:169], v[54:57]
	v_mfma_f32_16x16x32_bf16 v[46:49], v[142:145], v[166:169], v[46:49]
	v_mfma_f32_16x16x32_bf16 v[38:41], v[134:137], v[174:177], v[38:41]
	v_mfma_f32_16x16x32_bf16 v[50:53], v[142:145], v[174:177], v[50:53]
	v_mfma_f32_16x16x32_bf16 v[18:21], v[134:137], v[202:205], v[18:21]
	v_mfma_f32_16x16x32_bf16 v[34:37], v[142:145], v[202:205], v[34:37]
	v_mfma_f32_16x16x32_bf16 v[22:25], v[134:137], v[210:213], v[22:25]
	v_mfma_f32_16x16x32_bf16 v[74:77], v[142:145], v[210:213], v[74:77]
	v_mfma_f32_16x16x32_bf16 v[58:61], v[146:149], v[162:165], v[58:61]
	v_mfma_f32_16x16x32_bf16 v[30:33], v[154:157], v[162:165], v[30:33]
	v_mfma_f32_16x16x32_bf16 v[42:45], v[146:149], v[170:173], v[42:45]
	v_mfma_f32_16x16x32_bf16 v[6:9], v[154:157], v[170:173], v[6:9]
	v_mfma_f32_16x16x32_bf16 v[26:29], v[146:149], v[190:193], v[26:29]
	v_mfma_f32_16x16x32_bf16 v[10:13], v[154:157], v[190:193], v[10:13]
	v_mfma_f32_16x16x32_bf16 v[14:17], v[146:149], v[206:209], v[14:17]
	v_mfma_f32_16x16x32_bf16 v[2:5], v[154:157], v[206:209], v[2:5]
	v_mfma_f32_16x16x32_bf16 v[58:61], v[150:153], v[166:169], v[58:61]
	v_mfma_f32_16x16x32_bf16 v[30:33], v[158:161], v[166:169], v[30:33]
	v_mfma_f32_16x16x32_bf16 v[42:45], v[150:153], v[174:177], v[42:45]
	v_mfma_f32_16x16x32_bf16 v[6:9], v[158:161], v[174:177], v[6:9]
	v_mfma_f32_16x16x32_bf16 v[26:29], v[150:153], v[202:205], v[26:29]
	v_mfma_f32_16x16x32_bf16 v[10:13], v[158:161], v[202:205], v[10:13]
	v_mfma_f32_16x16x32_bf16 v[14:17], v[150:153], v[210:213], v[14:17]
	v_mfma_f32_16x16x32_bf16 v[2:5], v[158:161], v[210:213], v[2:5]
	s_barrier
	s_setprio 0
	s_add_i32 s31, s31, 2
	s_add_u32 s29, s29, 0x100
	s_addc_u32 s30, s30, 0
	s_cmp_gt_u32 s31, 29
	s_mov_b64 s[44:45], s[4:5]
	s_cbranch_scc0 .LBB0_1299
	s_and_b64 vcc, exec, s[48:49]
	s_cbranch_vccz .LBB0_1302
	s_barrier

; #define PG8_STAGE(bufoff, gbase, voff) do { _Pragma("unroll") for (int _i = 0; _i < 2; ++_i) \
;         __builtin_amdgcn_global_load_lds((const unsigned*)((const char*)(gbase) + (voff)[_i]), (LAS unsigned*)(lds + (bufoff) + ldsw + _i * 8192), 16, 0, 0); } while (0)
; #define PG8_LDA(dst, b, h) do { _Pragma("unroll") for (int m = 0; m < 4; ++m) _Pragma("unroll") for (int k = 0; k < 2; ++k) dst[m][k] = *(const LAS bf16x8*)(lds + PG8_SA(b, h) + aoff + m * 2048 + k * 1024); } while (0)
; #define PG8_LDB(dst, b, h) do { _Pragma("unroll") for (int n = 0; n < 2; ++n) _Pragma("unroll") for (int k = 0; k < 2; ++k) dst[n][k] = *(const LAS bf16x8*)(lds + PG8_SB(b, h) + boff + n * 2048 + k * 1024); } while (0)
; #define PG8_MMA(ai, bj, At, Bt) do { __builtin_amdgcn_s_setprio(1); _Pragma("unroll") for (int m = 0; m < 4; ++m) _Pragma("unroll") for (int n = 0; n < 2; ++n) _Pragma("unroll") for (int k = 0; k < 2; ++k) \
;         acc[ai][bj][m][n] = __builtin_amdgcn_mfma_f32_16x16x32_bf16(Bt[n][k], At[m][k], acc[ai][bj][m][n], 0, 0, 0); __builtin_amdgcn_s_setprio(0); } while (0)
; #define PG8_BAR __builtin_amdgcn_s_barrier()
; template <class Epi, int AMODE>
; __device__ __forceinline__ void gemm_phase(LAS unsigned char* lds, const Gemm g, const StaticOrder& S, const Epi& E, int stagger_us, int tid_in) {
;     ...
;         const bool has_next = S.next(ui + 1, nxt);
;         const char* nA = has_next ? Abase + (size_t)nxt.pm * tstepA : cA; const char* nB = has_next ? (const char*)g.Bt + (size_t)nxt.pn * tstepB : cB;
;         for (int t = 0; t < nt; t += 2) {
;             const bool last = (t == nt - 2);
;             const char* a1 = cA + (size_t)(t + 1) * kstep;
;             const char* a2 = last ? nA : cA + (size_t)(t + 2) * kstep; const char* b2 = last ? nB : cB + (size_t)(t + 2) * kstep;
;             const char* a3 = a2 + kstep; const char* b3 = b2 + kstep;
;             PG8_LDB(B0, 0, 0); PG8_LDB(B1, 0, 1); PG8_SCHED; PG8_LDA(At, 0, 0); PG8_STAGE(PG8_SA(1, 1), a1 + hstepA, voffA);
;             PG8_WAIT_V(8); PG8_WAIT_L(0); PG8_BAR; PG8_MMA(0, 0, At, B0); PG8_MMA(0, 1, At, B1); PG8_BAR; PG8_SCHED;
;             PG8_LDA(At, 0, 1); PG8_STAGE(PG8_SB(0, 0), b2, voffB); PG8_STAGE(PG8_SB(0, 1), b2 + hstepB, voffB); PG8_STAGE(PG8_SA(0, 0), a2, voffA);
;             PG8_WAIT_V(8); PG8_WAIT_L(0); PG8_BAR; PG8_MMA(1, 0, At, B0); PG8_MMA(1, 1, At, B1); PG8_BAR; PG8_SCHED;
.LBB0_1476:
	s_add_u32 s4, s54, 0x100
	s_addc_u32 s5, s55, 0
	s_add_i32 s30, 0, 0x10000
	s_cmpk_eq_i32 s29, 0x52
	s_cselect_b32 s57, s41, s5
	s_cselect_b32 s56, s40, s4
	s_cselect_b32 s7, s53, s28
	s_cselect_b32 s6, s52, s27
	s_add_i32 s34, 0, 0x14000
	v_add_u32_e32 v102, s30, v162
	v_add_u32_e32 v165, s34, v162
	ds_read_b128 v[66:69], v102
	ds_read_b128 v[70:73], v102 offset:1024
	ds_read_b128 v[74:77], v102 offset:2048
	ds_read_b128 v[102:105], v102 offset:3072
	ds_read_b128 v[152:155], v165
	ds_read_b128 v[156:159], v165 offset:1024
	ds_read_b128 v[166:169], v165 offset:2048
	ds_read_b128 v[170:173], v165 offset:3072
	v_lshl_add_u64 v[206:207], s[54:55], 0, v[148:149]
	s_add_i32 m0, s13, 0xc000
	ds_read_b128 v[174:177], v164
	ds_read_b128 v[178:181], v164 offset:1024
	ds_read_b128 v[182:185], v164 offset:2048
	ds_read_b128 v[186:189], v164 offset:3072
	ds_read_b128 v[190:193], v164 offset:4096
	ds_read_b128 v[194:197], v164 offset:5120
	ds_read_b128 v[198:201], v164 offset:6144
	ds_read_b128 v[202:205], v164 offset:7168
	global_load_lds_dwordx4 v[206:207], off
	v_lshl_add_u64 v[206:207], s[54:55], 0, v[150:151]
	s_add_i32 m0, s13, 0xe000
	s_nop 0
	global_load_lds_dwordx4 v[206:207], off
	s_waitcnt vmcnt(8)
	s_waitcnt lgkmcnt(0)
	s_setprio 1
	s_barrier
	v_mfma_f32_16x16x32_bf16 v[142:145], v[66:69], v[174:177], v[142:145]
	v_mfma_f32_16x16x32_bf16 v[138:141], v[74:77], v[174:177], v[138:141]
	v_mfma_f32_16x16x32_bf16 v[134:137], v[66:69], v[182:185], v[134:137]
	v_mfma_f32_16x16x32_bf16 v[130:133], v[74:77], v[182:185], v[130:133]
	v_mfma_f32_16x16x32_bf16 v[110:113], v[66:69], v[190:193], v[110:113]
	v_mfma_f32_16x16x32_bf16 v[106:109], v[74:77], v[190:193], v[106:109]
	v_mfma_f32_16x16x32_bf16 v[98:101], v[66:69], v[198:201], v[98:101]
	v_mfma_f32_16x16x32_bf16 v[94:97], v[74:77], v[198:201], v[94:97]
	v_mfma_f32_16x16x32_bf16 v[142:145], v[70:73], v[178:181], v[142:145]
	v_mfma_f32_16x16x32_bf16 v[138:141], v[102:105], v[178:181], v[138:141]
	v_mfma_f32_16x16x32_bf16 v[134:137], v[70:73], v[186:189], v[134:137]
	v_mfma_f32_16x16x32_bf16 v[130:133], v[102:105], v[186:189], v[130:133]
	v_mfma_f32_16x16x32_bf16 v[110:113], v[70:73], v[194:197], v[110:113]
	v_mfma_f32_16x16x32_bf16 v[106:109], v[102:105], v[194:197], v[106:109]
	v_mfma_f32_16x16x32_bf16 v[98:101], v[70:73], v[202:205], v[98:101]
	v_mfma_f32_16x16x32_bf16 v[94:97], v[102:105], v[202:205], v[94:97]
	v_mfma_f32_16x16x32_bf16 v[126:129], v[152:155], v[174:177], v[126:129]
	v_mfma_f32_16x16x32_bf16 v[122:125], v[166:169], v[174:177], v[122:125]
	v_mfma_f32_16x16x32_bf16 v[118:121], v[152:155], v[182:185], v[118:121]
	v_mfma_f32_16x16x32_bf16 v[114:117], v[166:169], v[182:185], v[114:117]
	v_mfma_f32_16x16x32_bf16 v[90:93], v[152:155], v[190:193], v[90:93]
	v_mfma_f32_16x16x32_bf16 v[86:89], v[166:169], v[190:193], v[86:89]
	v_mfma_f32_16x16x32_bf16 v[82:85], v[152:155], v[198:201], v[82:85]
	v_mfma_f32_16x16x32_bf16 v[78:81], v[166:169], v[198:201], v[78:81]
	v_mfma_f32_16x16x32_bf16 v[126:129], v[156:159], v[178:181], v[126:129]
	v_mfma_f32_16x16x32_bf16 v[122:125], v[170:173], v[178:181], v[122:125]
	v_mfma_f32_16x16x32_bf16 v[118:121], v[156:159], v[186:189], v[118:121]
	v_mfma_f32_16x16x32_bf16 v[114:117], v[170:173], v[186:189], v[114:117]
	v_mfma_f32_16x16x32_bf16 v[90:93], v[156:159], v[194:197], v[90:93]
	v_mfma_f32_16x16x32_bf16 v[86:89], v[170:173], v[194:197], v[86:89]
	v_mfma_f32_16x16x32_bf16 v[82:85], v[156:159], v[202:205], v[82:85]
	v_mfma_f32_16x16x32_bf16 v[78:81], v[170:173], v[202:205], v[78:81]
	s_barrier
	s_setprio 0
	s_add_i32 s30, s30, s12
	v_lshl_add_u64 v[206:207], s[6:7], 0, v[0:1]
	s_mov_b32 m0, s30
	ds_read_b128 v[174:177], v164 offset:16384
	ds_read_b128 v[178:181], v164 offset:17408
	ds_read_b128 v[182:185], v164 offset:18432
	ds_read_b128 v[186:189], v164 offset:19456
	ds_read_b128 v[190:193], v164 offset:20480
	ds_read_b128 v[194:197], v164 offset:21504
	ds_read_b128 v[198:201], v164 offset:22528
	ds_read_b128 v[202:205], v164 offset:23552
	global_load_lds_dwordx4 v[206:207], off
	s_add_i32 m0, s30, 0x2000
	s_add_u32 s30, s6, 0x158000
	v_lshl_add_u64 v[208:209], s[6:7], 0, v[146:147]
	s_addc_u32 s31, s7, 0
	s_add_i32 s34, s34, s12
	global_load_lds_dwordx4 v[208:209], off
	v_lshl_add_u64 v[210:211], s[30:31], 0, v[0:1]
	s_mov_b32 m0, s34
	v_lshl_add_u64 v[212:213], s[56:57], 0, v[146:147]
	global_load_lds_dwordx4 v[210:211], off
	v_lshl_add_u64 v[210:211], s[30:31], 0, v[146:147]
	s_add_i32 m0, s34, 0x2000
	s_nop 0
	global_load_lds_dwordx4 v[210:211], off
	v_lshl_add_u64 v[210:211], s[56:57], 0, v[0:1]
	s_mov_b32 m0, s13
	s_nop 0
	global_load_lds_dwordx4 v[210:211], off
	s_mov_b32 m0, s24
	s_nop 0
	global_load_lds_dwordx4 v[212:213], off
	s_waitcnt vmcnt(8)
	s_waitcnt lgkmcnt(0)
	s_setprio 1
	s_barrier
; #define PG8_STAGE(bufoff, gbase, voff) do { _Pragma("unroll") for (int _i = 0; _i < 2; ++_i) \
;         __builtin_amdgcn_global_load_lds((const unsigned*)((const char*)(gbase) + (voff)[_i]), (LAS unsigned*)(lds + (bufoff) + ldsw + _i * 8192), 16, 0, 0); } while (0)
; #define PG8_LDA(dst, b, h) do { _Pragma("unroll") for (int m = 0; m < 4; ++m) _Pragma("unroll") for (int k = 0; k < 2; ++k) dst[m][k] = *(const LAS bf16x8*)(lds + PG8_SA(b, h) + aoff + m * 2048 + k * 1024); } while (0)
; #define PG8_LDB(dst, b, h) do { _Pragma("unroll") for (int n = 0; n < 2; ++n) _Pragma("unroll") for (int k = 0; k < 2; ++k) dst[n][k] = *(const LAS bf16x8*)(lds + PG8_SB(b, h) + boff + n * 2048 + k * 1024); } while (0)
; #define PG8_MMA(ai, bj, At, Bt) do { __builtin_amdgcn_s_setprio(1); _Pragma("unroll") for (int m = 0; m < 4; ++m) _Pragma("unroll") for (int n = 0; n < 2; ++n) _Pragma("unroll") for (int k = 0; k < 2; ++k) \
;         acc[ai][bj][m][n] = __builtin_amdgcn_mfma_f32_16x16x32_bf16(Bt[n][k], At[m][k], acc[ai][bj][m][n], 0, 0, 0); __builtin_amdgcn_s_setprio(0); } while (0)
; #define PG8_WAIT_V(n) asm volatile("s_waitcnt vmcnt(" #n ")" ::: "memory")
; #define PG8_WAIT_L(n) asm volatile("s_waitcnt lgkmcnt(" #n ")" ::: "memory")
; #define PG8_BAR __builtin_amdgcn_s_barrier()
; #define PG8_SCHED __builtin_amdgcn_sched_barrier(0)
; template <class Epi, int AMODE>
; __device__ __forceinline__ void gemm_phase(LAS unsigned char* lds, const Gemm g, const StaticOrder& S, const Epi& E, int stagger_us, int tid_in) {
;     ...
;             PG8_WAIT_V(8); PG8_WAIT_L(0); PG8_BAR; PG8_MMA(1, 0, At, B0); PG8_MMA(1, 1, At, B1); PG8_BAR; PG8_SCHED;
;             PG8_LDB(B0, 1, 0); PG8_LDB(B1, 1, 1); PG8_SCHED; PG8_LDA(At, 1, 0); PG8_STAGE(PG8_SA(0, 1), a2 + hstepA, voffA);
;             PG8_WAIT_V(8); PG8_WAIT_L(0); PG8_BAR; PG8_MMA(0, 0, At, B0); PG8_MMA(0, 1, At, B1); PG8_BAR; PG8_SCHED;
	v_mfma_f32_16x16x32_bf16 v[62:65], v[66:69], v[174:177], v[62:65]
	v_mfma_f32_16x16x32_bf16 v[58:61], v[74:77], v[174:177], v[58:61]
	v_mfma_f32_16x16x32_bf16 v[54:57], v[66:69], v[182:185], v[54:57]
	v_mfma_f32_16x16x32_bf16 v[50:53], v[74:77], v[182:185], v[50:53]
	v_mfma_f32_16x16x32_bf16 v[30:33], v[66:69], v[190:193], v[30:33]
	v_mfma_f32_16x16x32_bf16 v[26:29], v[74:77], v[190:193], v[26:29]
	v_mfma_f32_16x16x32_bf16 v[22:25], v[66:69], v[198:201], v[22:25]
	v_mfma_f32_16x16x32_bf16 v[10:13], v[74:77], v[198:201], v[10:13]
	v_mfma_f32_16x16x32_bf16 v[62:65], v[70:73], v[178:181], v[62:65]
	v_mfma_f32_16x16x32_bf16 v[58:61], v[102:105], v[178:181], v[58:61]
	v_mfma_f32_16x16x32_bf16 v[54:57], v[70:73], v[186:189], v[54:57]
	v_mfma_f32_16x16x32_bf16 v[50:53], v[102:105], v[186:189], v[50:53]
	v_mfma_f32_16x16x32_bf16 v[30:33], v[70:73], v[194:197], v[30:33]
	v_mfma_f32_16x16x32_bf16 v[26:29], v[102:105], v[194:197], v[26:29]
	v_mfma_f32_16x16x32_bf16 v[22:25], v[70:73], v[202:205], v[22:25]
	v_mfma_f32_16x16x32_bf16 v[10:13], v[102:105], v[202:205], v[10:13]
	v_mfma_f32_16x16x32_bf16 v[46:49], v[152:155], v[174:177], v[46:49]
	v_mfma_f32_16x16x32_bf16 v[42:45], v[166:169], v[174:177], v[42:45]
	v_mfma_f32_16x16x32_bf16 v[38:41], v[152:155], v[182:185], v[38:41]
	v_mfma_f32_16x16x32_bf16 v[34:37], v[166:169], v[182:185], v[34:37]
	v_mfma_f32_16x16x32_bf16 v[18:21], v[152:155], v[190:193], v[18:21]
	v_mfma_f32_16x16x32_bf16 v[14:17], v[166:169], v[190:193], v[14:17]
	v_mfma_f32_16x16x32_bf16 v[6:9], v[152:155], v[198:201], v[6:9]
	v_mfma_f32_16x16x32_bf16 v[2:5], v[166:169], v[198:201], v[2:5]
	v_mfma_f32_16x16x32_bf16 v[46:49], v[156:159], v[178:181], v[46:49]
	v_mfma_f32_16x16x32_bf16 v[42:45], v[170:173], v[178:181], v[42:45]
	v_mfma_f32_16x16x32_bf16 v[38:41], v[156:159], v[186:189], v[38:41]
	v_mfma_f32_16x16x32_bf16 v[34:37], v[170:173], v[186:189], v[34:37]
	v_mfma_f32_16x16x32_bf16 v[18:21], v[156:159], v[194:197], v[18:21]
	v_mfma_f32_16x16x32_bf16 v[14:17], v[170:173], v[194:197], v[14:17]
	v_mfma_f32_16x16x32_bf16 v[6:9], v[156:159], v[202:205], v[6:9]
	v_mfma_f32_16x16x32_bf16 v[2:5], v[170:173], v[202:205], v[2:5]
	s_barrier
	s_setprio 0
	s_add_i32 s34, 0, 0x18000
	s_add_i32 s35, 0, 0x1c000
	v_add_u32_e32 v102, s34, v162
	v_add_u32_e32 v165, s35, v162
	ds_read_b128 v[66:69], v102
	ds_read_b128 v[70:73], v102 offset:1024
	ds_read_b128 v[74:77], v102 offset:2048
	ds_read_b128 v[102:105], v102 offset:3072
	ds_read_b128 v[152:155], v165
	ds_read_b128 v[156:159], v165 offset:1024
	ds_read_b128 v[166:169], v165 offset:2048
	ds_read_b128 v[170:173], v165 offset:3072
	s_add_u32 s30, s56, 0x158000
	s_addc_u32 s31, s57, 0
	s_mov_b32 m0, s25
	v_lshl_add_u64 v[214:215], s[30:31], 0, v[0:1]
	ds_read_b128 v[174:177], v164 offset:32768
	ds_read_b128 v[178:181], v164 offset:33792
	ds_read_b128 v[182:185], v164 offset:34816
	ds_read_b128 v[186:189], v164 offset:35840
	ds_read_b128 v[190:193], v164 offset:36864
	ds_read_b128 v[194:197], v164 offset:37888
	ds_read_b128 v[198:201], v164 offset:38912
	ds_read_b128 v[202:205], v164 offset:39936
	global_load_lds_dwordx4 v[214:215], off
	v_lshl_add_u64 v[214:215], s[30:31], 0, v[146:147]
	s_mov_b32 m0, s66
	s_nop 0
	global_load_lds_dwordx4 v[214:215], off
	s_waitcnt vmcnt(8)
	s_waitcnt lgkmcnt(0)
	s_setprio 1
	s_barrier
	v_mfma_f32_16x16x32_bf16 v[142:145], v[66:69], v[174:177], v[142:145]
	v_mfma_f32_16x16x32_bf16 v[138:141], v[74:77], v[174:177], v[138:141]
	v_mfma_f32_16x16x32_bf16 v[134:137], v[66:69], v[182:185], v[134:137]
	v_mfma_f32_16x16x32_bf16 v[130:133], v[74:77], v[182:185], v[130:133]
	v_mfma_f32_16x16x32_bf16 v[110:113], v[66:69], v[190:193], v[110:113]
	v_mfma_f32_16x16x32_bf16 v[106:109], v[74:77], v[190:193], v[106:109]
	v_mfma_f32_16x16x32_bf16 v[98:101], v[66:69], v[198:201], v[98:101]
	v_mfma_f32_16x16x32_bf16 v[94:97], v[74:77], v[198:201], v[94:97]
	v_mfma_f32_16x16x32_bf16 v[142:145], v[70:73], v[178:181], v[142:145]
	v_mfma_f32_16x16x32_bf16 v[138:141], v[102:105], v[178:181], v[138:141]
	v_mfma_f32_16x16x32_bf16 v[134:137], v[70:73], v[186:189], v[134:137]
	v_mfma_f32_16x16x32_bf16 v[130:133], v[102:105], v[186:189], v[130:133]
	v_mfma_f32_16x16x32_bf16 v[110:113], v[70:73], v[194:197], v[110:113]
	v_mfma_f32_16x16x32_bf16 v[106:109], v[102:105], v[194:197], v[106:109]
	v_mfma_f32_16x16x32_bf16 v[98:101], v[70:73], v[202:205], v[98:101]
	v_mfma_f32_16x16x32_bf16 v[94:97], v[102:105], v[202:205], v[94:97]
	v_mfma_f32_16x16x32_bf16 v[126:129], v[152:155], v[174:177], v[126:129]
	v_mfma_f32_16x16x32_bf16 v[122:125], v[166:169], v[174:177], v[122:125]
	v_mfma_f32_16x16x32_bf16 v[118:121], v[152:155], v[182:185], v[118:121]
	v_mfma_f32_16x16x32_bf16 v[114:117], v[166:169], v[182:185], v[114:117]
	v_mfma_f32_16x16x32_bf16 v[90:93], v[152:155], v[190:193], v[90:93]
	v_mfma_f32_16x16x32_bf16 v[86:89], v[166:169], v[190:193], v[86:89]
	v_mfma_f32_16x16x32_bf16 v[82:85], v[152:155], v[198:201], v[82:85]
	v_mfma_f32_16x16x32_bf16 v[78:81], v[166:169], v[198:201], v[78:81]
	v_mfma_f32_16x16x32_bf16 v[126:129], v[156:159], v[178:181], v[126:129]
	v_mfma_f32_16x16x32_bf16 v[122:125], v[170:173], v[178:181], v[122:125]
	v_mfma_f32_16x16x32_bf16 v[118:121], v[156:159], v[186:189], v[118:121]
	v_mfma_f32_16x16x32_bf16 v[114:117], v[170:173], v[186:189], v[114:117]
	v_mfma_f32_16x16x32_bf16 v[90:93], v[156:159], v[194:197], v[90:93]
	v_mfma_f32_16x16x32_bf16 v[86:89], v[170:173], v[194:197], v[86:89]
	v_mfma_f32_16x16x32_bf16 v[82:85], v[156:159], v[202:205], v[82:85]
	v_mfma_f32_16x16x32_bf16 v[78:81], v[170:173], v[202:205], v[78:81]
	s_barrier
; #define PG8_STAGE(bufoff, gbase, voff) do { _Pragma("unroll") for (int _i = 0; _i < 2; ++_i) \
;         __builtin_amdgcn_global_load_lds((const unsigned*)((const char*)(gbase) + (voff)[_i]), (LAS unsigned*)(lds + (bufoff) + ldsw + _i * 8192), 16, 0, 0); } while (0)
; #define PG8_LDA(dst, b, h) do { _Pragma("unroll") for (int m = 0; m < 4; ++m) _Pragma("unroll") for (int k = 0; k < 2; ++k) dst[m][k] = *(const LAS bf16x8*)(lds + PG8_SA(b, h) + aoff + m * 2048 + k * 1024); } while (0)
; #define PG8_MMA(ai, bj, At, Bt) do { __builtin_amdgcn_s_setprio(1); _Pragma("unroll") for (int m = 0; m < 4; ++m) _Pragma("unroll") for (int n = 0; n < 2; ++n) _Pragma("unroll") for (int k = 0; k < 2; ++k) \
;         acc[ai][bj][m][n] = __builtin_amdgcn_mfma_f32_16x16x32_bf16(Bt[n][k], At[m][k], acc[ai][bj][m][n], 0, 0, 0); __builtin_amdgcn_s_setprio(0); } while (0)
; #define PG8_WAIT_V(n) asm volatile("s_waitcnt vmcnt(" #n ")" ::: "memory")
; #define PG8_WAIT_L(n) asm volatile("s_waitcnt lgkmcnt(" #n ")" ::: "memory")
; #define PG8_BAR __builtin_amdgcn_s_barrier()
; #define PG8_SCHED __builtin_amdgcn_sched_barrier(0)
; template <class Epi, int AMODE>
; __device__ __forceinline__ void gemm_phase(LAS unsigned char* lds, const Gemm g, const StaticOrder& S, const Epi& E, int stagger_us, int tid_in) {
;     ...
;             PG8_LDA(At, 1, 1); PG8_STAGE(PG8_SB(1, 0), b3, voffB); PG8_STAGE(PG8_SB(1, 1), b3 + hstepB, voffB); PG8_STAGE(PG8_SA(1, 0), a3, voffA);
;             PG8_WAIT_V(8); PG8_WAIT_L(0); PG8_BAR; PG8_MMA(1, 0, At, B0); PG8_MMA(1, 1, At, B1); PG8_BAR; PG8_SCHED;
;         }
;         if (wr == 0) PG8_BAR;
	s_setprio 0
	s_add_i32 s30, s34, s12
	v_lshl_add_u64 v[206:207], v[206:207], 0, s[74:75]
	s_mov_b32 m0, s30
	ds_read_b128 v[174:177], v164 offset:49152
	ds_read_b128 v[178:181], v164 offset:50176
	ds_read_b128 v[182:185], v164 offset:51200
	ds_read_b128 v[186:189], v164 offset:52224
	ds_read_b128 v[190:193], v164 offset:53248
	ds_read_b128 v[194:197], v164 offset:54272
	ds_read_b128 v[198:201], v164 offset:55296
	ds_read_b128 v[202:205], v164 offset:56320
	global_load_lds_dwordx4 v[206:207], off
	s_add_i32 m0, s30, 0x2000
	s_add_u32 s6, s6, 0x158080
	v_lshl_add_u64 v[206:207], v[208:209], 0, s[74:75]
	s_addc_u32 s7, s7, 0
	s_add_i32 s30, s35, s12
	global_load_lds_dwordx4 v[206:207], off
	v_lshl_add_u64 v[206:207], s[6:7], 0, v[0:1]
	s_mov_b32 m0, s30
	s_nop 0
	global_load_lds_dwordx4 v[206:207], off
	v_lshl_add_u64 v[206:207], s[6:7], 0, v[146:147]
	s_add_i32 m0, s30, 0x2000
	s_nop 0
	global_load_lds_dwordx4 v[206:207], off
	v_lshl_add_u64 v[206:207], v[210:211], 0, s[74:75]
	s_mov_b32 m0, s67
	s_nop 0
	global_load_lds_dwordx4 v[206:207], off
	v_lshl_add_u64 v[206:207], v[212:213], 0, s[74:75]
	s_mov_b32 m0, s69
	s_nop 0
	global_load_lds_dwordx4 v[206:207], off
	s_waitcnt vmcnt(8)
	s_waitcnt lgkmcnt(0)
	s_setprio 1
	s_barrier
	v_mfma_f32_16x16x32_bf16 v[62:65], v[66:69], v[174:177], v[62:65]
	v_mfma_f32_16x16x32_bf16 v[58:61], v[74:77], v[174:177], v[58:61]
	v_mfma_f32_16x16x32_bf16 v[54:57], v[66:69], v[182:185], v[54:57]
	v_mfma_f32_16x16x32_bf16 v[50:53], v[74:77], v[182:185], v[50:53]
	v_mfma_f32_16x16x32_bf16 v[30:33], v[66:69], v[190:193], v[30:33]
	v_mfma_f32_16x16x32_bf16 v[26:29], v[74:77], v[190:193], v[26:29]
	v_mfma_f32_16x16x32_bf16 v[22:25], v[66:69], v[198:201], v[22:25]
	v_mfma_f32_16x16x32_bf16 v[10:13], v[74:77], v[198:201], v[10:13]
	v_mfma_f32_16x16x32_bf16 v[62:65], v[70:73], v[178:181], v[62:65]
	v_mfma_f32_16x16x32_bf16 v[58:61], v[102:105], v[178:181], v[58:61]
	v_mfma_f32_16x16x32_bf16 v[54:57], v[70:73], v[186:189], v[54:57]
	v_mfma_f32_16x16x32_bf16 v[50:53], v[102:105], v[186:189], v[50:53]
	v_mfma_f32_16x16x32_bf16 v[30:33], v[70:73], v[194:197], v[30:33]
	v_mfma_f32_16x16x32_bf16 v[26:29], v[102:105], v[194:197], v[26:29]
	v_mfma_f32_16x16x32_bf16 v[22:25], v[70:73], v[202:205], v[22:25]
	v_mfma_f32_16x16x32_bf16 v[10:13], v[102:105], v[202:205], v[10:13]
	v_mfma_f32_16x16x32_bf16 v[46:49], v[152:155], v[174:177], v[46:49]
	v_mfma_f32_16x16x32_bf16 v[42:45], v[166:169], v[174:177], v[42:45]
	v_mfma_f32_16x16x32_bf16 v[38:41], v[152:155], v[182:185], v[38:41]
	v_mfma_f32_16x16x32_bf16 v[34:37], v[166:169], v[182:185], v[34:37]
	v_mfma_f32_16x16x32_bf16 v[18:21], v[152:155], v[190:193], v[18:21]
	v_mfma_f32_16x16x32_bf16 v[14:17], v[166:169], v[190:193], v[14:17]
	v_mfma_f32_16x16x32_bf16 v[6:9], v[152:155], v[198:201], v[6:9]
	v_mfma_f32_16x16x32_bf16 v[2:5], v[166:169], v[198:201], v[2:5]
	v_mfma_f32_16x16x32_bf16 v[46:49], v[156:159], v[178:181], v[46:49]
	v_mfma_f32_16x16x32_bf16 v[42:45], v[170:173], v[178:181], v[42:45]
	v_mfma_f32_16x16x32_bf16 v[38:41], v[156:159], v[186:189], v[38:41]
	v_mfma_f32_16x16x32_bf16 v[34:37], v[170:173], v[186:189], v[34:37]
	v_mfma_f32_16x16x32_bf16 v[18:21], v[156:159], v[194:197], v[18:21]
	v_mfma_f32_16x16x32_bf16 v[14:17], v[170:173], v[194:197], v[14:17]
	v_mfma_f32_16x16x32_bf16 v[6:9], v[156:159], v[202:205], v[6:9]
	v_mfma_f32_16x16x32_bf16 v[2:5], v[170:173], v[202:205], v[2:5]
	s_barrier
	s_setprio 0
	s_add_i32 s29, s29, 2
	s_add_u32 s27, s27, 0x100
	s_addc_u32 s28, s28, 0
	s_cmpk_gt_u32 s29, 0x53
	s_mov_b64 s[54:55], s[4:5]
	s_cbranch_scc0 .LBB0_1476
	s_and_b64 vcc, exec, s[46:47]
	s_cbranch_vccz .LBB0_1479
	s_barrier

; #define PG8_STAGE(bufoff, gbase, voff) do { _Pragma("unroll") for (int _i = 0; _i < 2; ++_i) \
;         __builtin_amdgcn_global_load_lds((const unsigned*)((const char*)(gbase) + (voff)[_i]), (LAS unsigned*)(lds + (bufoff) + ldsw + _i * 8192), 16, 0, 0); } while (0)
; #define PG8_LDA(dst, b, h) do { _Pragma("unroll") for (int m = 0; m < 4; ++m) _Pragma("unroll") for (int k = 0; k < 2; ++k) dst[m][k] = *(const LAS bf16x8*)(lds + PG8_SA(b, h) + aoff + m * 2048 + k * 1024); } while (0)
; #define PG8_LDB(dst, b, h) do { _Pragma("unroll") for (int n = 0; n < 2; ++n) _Pragma("unroll") for (int k = 0; k < 2; ++k) dst[n][k] = *(const LAS bf16x8*)(lds + PG8_SB(b, h) + boff + n * 2048 + k * 1024); } while (0)
; #define PG8_MMA(ai, bj, At, Bt) do { __builtin_amdgcn_s_setprio(1); _Pragma("unroll") for (int m = 0; m < 4; ++m) _Pragma("unroll") for (int n = 0; n < 2; ++n) _Pragma("unroll") for (int k = 0; k < 2; ++k) \
;         acc[ai][bj][m][n] = __builtin_amdgcn_mfma_f32_16x16x32_bf16(Bt[n][k], At[m][k], acc[ai][bj][m][n], 0, 0, 0); __builtin_amdgcn_s_setprio(0); } while (0)
; #define PG8_BAR __builtin_amdgcn_s_barrier()
; template <class Epi, int AMODE>
; __device__ __forceinline__ void gemm_phase(LAS unsigned char* lds, const Gemm g, const StaticOrder& S, const Epi& E, int stagger_us, int tid_in) {
;     ...
;         const bool has_next = S.next(ui + 1, nxt);
;         const char* nA = has_next ? Abase + (size_t)nxt.pm * tstepA : cA; const char* nB = has_next ? (const char*)g.Bt + (size_t)nxt.pn * tstepB : cB;
;         for (int t = 0; t < nt; t += 2) {
;             const bool last = (t == nt - 2);
;             const char* a1 = cA + (size_t)(t + 1) * kstep;
;             const char* a2 = last ? nA : cA + (size_t)(t + 2) * kstep; const char* b2 = last ? nB : cB + (size_t)(t + 2) * kstep;
;             const char* a3 = a2 + kstep; const char* b3 = b2 + kstep;
;             PG8_LDB(B0, 0, 0); PG8_LDB(B1, 0, 1); PG8_SCHED; PG8_LDA(At, 0, 0); PG8_STAGE(PG8_SA(1, 1), a1 + hstepA, voffA);
;             PG8_WAIT_V(8); PG8_WAIT_L(0); PG8_BAR; PG8_MMA(0, 0, At, B0); PG8_MMA(0, 1, At, B1); PG8_BAR; PG8_SCHED;
;             PG8_LDA(At, 0, 1); PG8_STAGE(PG8_SB(0, 0), b2, voffB); PG8_STAGE(PG8_SB(0, 1), b2 + hstepB, voffB); PG8_STAGE(PG8_SA(0, 0), a2, voffA);
;             PG8_WAIT_V(8); PG8_WAIT_L(0); PG8_BAR; PG8_MMA(1, 0, At, B0); PG8_MMA(1, 1, At, B1); PG8_BAR; PG8_SCHED;
.LBB0_1498:
	s_add_u32 s4, s46, 0x100
	s_addc_u32 s5, s47, 0
	s_add_i32 s30, 0, 0x10000
	s_cmpk_eq_i32 s29, 0x52
	s_cselect_b32 s59, s41, s5
	s_cselect_b32 s58, s40, s4
	s_cselect_b32 s7, s57, s28
	s_cselect_b32 s6, s56, s27
	s_add_i32 s34, 0, 0x14000
	v_add_u32_e32 v62, s30, v209
	v_add_u32_e32 v158, s34, v209
	ds_read_b128 v[50:53], v62
	ds_read_b128 v[54:57], v62 offset:1024
	ds_read_b128 v[58:61], v62 offset:2048
	ds_read_b128 v[62:65], v62 offset:3072
	ds_read_b128 v[146:149], v158
	ds_read_b128 v[150:153], v158 offset:1024
	ds_read_b128 v[154:157], v158 offset:2048
	ds_read_b128 v[158:161], v158 offset:3072
	v_lshl_add_u64 v[200:201], s[46:47], 0, v[176:177]
	s_add_i32 m0, s13, 0xc000
	ds_read_b128 v[162:165], v215
	ds_read_b128 v[166:169], v215 offset:1024
	ds_read_b128 v[170:173], v215 offset:2048
	ds_read_b128 v[180:183], v215 offset:3072
	ds_read_b128 v[184:187], v215 offset:4096
	ds_read_b128 v[188:191], v215 offset:5120
	ds_read_b128 v[192:195], v215 offset:6144
	ds_read_b128 v[196:199], v215 offset:7168
	global_load_lds_dwordx4 v[200:201], off
	v_lshl_add_u64 v[200:201], s[46:47], 0, v[178:179]
	s_add_i32 m0, s13, 0xe000
	s_nop 0
	global_load_lds_dwordx4 v[200:201], off
	s_waitcnt vmcnt(8)
	s_waitcnt lgkmcnt(0)
	s_setprio 1
	s_barrier
	v_mfma_f32_16x16x32_bf16 v[142:145], v[50:53], v[162:165], v[142:145]
	v_mfma_f32_16x16x32_bf16 v[138:141], v[58:61], v[162:165], v[138:141]
	v_mfma_f32_16x16x32_bf16 v[126:129], v[50:53], v[170:173], v[126:129]
	v_mfma_f32_16x16x32_bf16 v[122:125], v[58:61], v[170:173], v[122:125]
	v_mfma_f32_16x16x32_bf16 v[110:113], v[50:53], v[184:187], v[110:113]
	v_mfma_f32_16x16x32_bf16 v[106:109], v[58:61], v[184:187], v[106:109]
	v_mfma_f32_16x16x32_bf16 v[94:97], v[50:53], v[192:195], v[94:97]
	v_mfma_f32_16x16x32_bf16 v[90:93], v[58:61], v[192:195], v[90:93]
	v_mfma_f32_16x16x32_bf16 v[142:145], v[54:57], v[166:169], v[142:145]
	v_mfma_f32_16x16x32_bf16 v[138:141], v[62:65], v[166:169], v[138:141]
	v_mfma_f32_16x16x32_bf16 v[126:129], v[54:57], v[180:183], v[126:129]
	v_mfma_f32_16x16x32_bf16 v[122:125], v[62:65], v[180:183], v[122:125]
	v_mfma_f32_16x16x32_bf16 v[110:113], v[54:57], v[188:191], v[110:113]
	v_mfma_f32_16x16x32_bf16 v[106:109], v[62:65], v[188:191], v[106:109]
	v_mfma_f32_16x16x32_bf16 v[94:97], v[54:57], v[196:199], v[94:97]
	v_mfma_f32_16x16x32_bf16 v[90:93], v[62:65], v[196:199], v[90:93]
	v_mfma_f32_16x16x32_bf16 v[134:137], v[146:149], v[162:165], v[134:137]
	v_mfma_f32_16x16x32_bf16 v[130:133], v[154:157], v[162:165], v[130:133]
	v_mfma_f32_16x16x32_bf16 v[118:121], v[146:149], v[170:173], v[118:121]
	v_mfma_f32_16x16x32_bf16 v[114:117], v[154:157], v[170:173], v[114:117]
	v_mfma_f32_16x16x32_bf16 v[102:105], v[146:149], v[184:187], v[102:105]
	v_mfma_f32_16x16x32_bf16 v[98:101], v[154:157], v[184:187], v[98:101]
	v_mfma_f32_16x16x32_bf16 v[86:89], v[146:149], v[192:195], v[86:89]
	v_mfma_f32_16x16x32_bf16 v[82:85], v[154:157], v[192:195], v[82:85]
	v_mfma_f32_16x16x32_bf16 v[134:137], v[150:153], v[166:169], v[134:137]
	v_mfma_f32_16x16x32_bf16 v[130:133], v[158:161], v[166:169], v[130:133]
	v_mfma_f32_16x16x32_bf16 v[118:121], v[150:153], v[180:183], v[118:121]
	v_mfma_f32_16x16x32_bf16 v[114:117], v[158:161], v[180:183], v[114:117]
	v_mfma_f32_16x16x32_bf16 v[102:105], v[150:153], v[188:191], v[102:105]
	v_mfma_f32_16x16x32_bf16 v[98:101], v[158:161], v[188:191], v[98:101]
	v_mfma_f32_16x16x32_bf16 v[86:89], v[150:153], v[196:199], v[86:89]
	v_mfma_f32_16x16x32_bf16 v[82:85], v[158:161], v[196:199], v[82:85]
	s_barrier
	s_setprio 0
	s_add_i32 s30, s30, s12
	v_lshl_add_u64 v[200:201], s[6:7], 0, v[0:1]
	s_mov_b32 m0, s30
	ds_read_b128 v[162:165], v215 offset:16384
	ds_read_b128 v[166:169], v215 offset:17408
	ds_read_b128 v[170:173], v215 offset:18432
	ds_read_b128 v[180:183], v215 offset:19456
	ds_read_b128 v[184:187], v215 offset:20480
	ds_read_b128 v[188:191], v215 offset:21504
	ds_read_b128 v[192:195], v215 offset:22528
	ds_read_b128 v[196:199], v215 offset:23552
	global_load_lds_dwordx4 v[200:201], off
	s_add_i32 m0, s30, 0x2000
	s_add_u32 s30, s6, 0x158000
	v_lshl_add_u64 v[202:203], s[6:7], 0, v[174:175]
	s_addc_u32 s31, s7, 0
	s_add_i32 s34, s34, s12
	global_load_lds_dwordx4 v[202:203], off
	v_lshl_add_u64 v[204:205], s[30:31], 0, v[0:1]
	s_mov_b32 m0, s34
	v_lshl_add_u64 v[206:207], s[58:59], 0, v[174:175]
	global_load_lds_dwordx4 v[204:205], off
	v_lshl_add_u64 v[204:205], s[30:31], 0, v[174:175]
	s_add_i32 m0, s34, 0x2000
	s_nop 0
	global_load_lds_dwordx4 v[204:205], off
	v_lshl_add_u64 v[204:205], s[58:59], 0, v[0:1]
	s_mov_b32 m0, s13
	s_nop 0
	global_load_lds_dwordx4 v[204:205], off
	s_mov_b32 m0, s24
	s_nop 0
	global_load_lds_dwordx4 v[206:207], off
	s_waitcnt vmcnt(8)
	s_waitcnt lgkmcnt(0)
	s_setprio 1
	s_barrier
; #define PG8_STAGE(bufoff, gbase, voff) do { _Pragma("unroll") for (int _i = 0; _i < 2; ++_i) \
;         __builtin_amdgcn_global_load_lds((const unsigned*)((const char*)(gbase) + (voff)[_i]), (LAS unsigned*)(lds + (bufoff) + ldsw + _i * 8192), 16, 0, 0); } while (0)
; #define PG8_LDA(dst, b, h) do { _Pragma("unroll") for (int m = 0; m < 4; ++m) _Pragma("unroll") for (int k = 0; k < 2; ++k) dst[m][k] = *(const LAS bf16x8*)(lds + PG8_SA(b, h) + aoff + m * 2048 + k * 1024); } while (0)
; #define PG8_LDB(dst, b, h) do { _Pragma("unroll") for (int n = 0; n < 2; ++n) _Pragma("unroll") for (int k = 0; k < 2; ++k) dst[n][k] = *(const LAS bf16x8*)(lds + PG8_SB(b, h) + boff + n * 2048 + k * 1024); } while (0)
; #define PG8_MMA(ai, bj, At, Bt) do { __builtin_amdgcn_s_setprio(1); _Pragma("unroll") for (int m = 0; m < 4; ++m) _Pragma("unroll") for (int n = 0; n < 2; ++n) _Pragma("unroll") for (int k = 0; k < 2; ++k) \
;         acc[ai][bj][m][n] = __builtin_amdgcn_mfma_f32_16x16x32_bf16(Bt[n][k], At[m][k], acc[ai][bj][m][n], 0, 0, 0); __builtin_amdgcn_s_setprio(0); } while (0)
; #define PG8_WAIT_V(n) asm volatile("s_waitcnt vmcnt(" #n ")" ::: "memory")
; #define PG8_WAIT_L(n) asm volatile("s_waitcnt lgkmcnt(" #n ")" ::: "memory")
; #define PG8_BAR __builtin_amdgcn_s_barrier()
; #define PG8_SCHED __builtin_amdgcn_sched_barrier(0)
; template <class Epi, int AMODE>
; __device__ __forceinline__ void gemm_phase(LAS unsigned char* lds, const Gemm g, const StaticOrder& S, const Epi& E, int stagger_us, int tid_in) {
;     ...
;             PG8_WAIT_V(8); PG8_WAIT_L(0); PG8_BAR; PG8_MMA(1, 0, At, B0); PG8_MMA(1, 1, At, B1); PG8_BAR; PG8_SCHED;
;             PG8_LDB(B0, 1, 0); PG8_LDB(B1, 1, 1); PG8_SCHED; PG8_LDA(At, 1, 0); PG8_STAGE(PG8_SA(0, 1), a2 + hstepA, voffA);
;             PG8_WAIT_V(8); PG8_WAIT_L(0); PG8_BAR; PG8_MMA(0, 0, At, B0); PG8_MMA(0, 1, At, B1); PG8_BAR; PG8_SCHED;
	v_mfma_f32_16x16x32_bf16 v[78:81], v[50:53], v[162:165], v[78:81]
	v_mfma_f32_16x16x32_bf16 v[74:77], v[58:61], v[162:165], v[74:77]
	v_mfma_f32_16x16x32_bf16 v[46:49], v[50:53], v[170:173], v[46:49]
	v_mfma_f32_16x16x32_bf16 v[42:45], v[58:61], v[170:173], v[42:45]
	v_mfma_f32_16x16x32_bf16 v[30:33], v[50:53], v[184:187], v[30:33]
	v_mfma_f32_16x16x32_bf16 v[26:29], v[58:61], v[184:187], v[26:29]
	v_mfma_f32_16x16x32_bf16 v[14:17], v[50:53], v[192:195], v[14:17]
	v_mfma_f32_16x16x32_bf16 v[10:13], v[58:61], v[192:195], v[10:13]
	v_mfma_f32_16x16x32_bf16 v[78:81], v[54:57], v[166:169], v[78:81]
	v_mfma_f32_16x16x32_bf16 v[74:77], v[62:65], v[166:169], v[74:77]
	v_mfma_f32_16x16x32_bf16 v[46:49], v[54:57], v[180:183], v[46:49]
	v_mfma_f32_16x16x32_bf16 v[42:45], v[62:65], v[180:183], v[42:45]
	v_mfma_f32_16x16x32_bf16 v[30:33], v[54:57], v[188:191], v[30:33]
	v_mfma_f32_16x16x32_bf16 v[26:29], v[62:65], v[188:191], v[26:29]
	v_mfma_f32_16x16x32_bf16 v[14:17], v[54:57], v[196:199], v[14:17]
	v_mfma_f32_16x16x32_bf16 v[10:13], v[62:65], v[196:199], v[10:13]
	v_mfma_f32_16x16x32_bf16 v[38:41], v[146:149], v[170:173], v[38:41]
	v_mfma_f32_16x16x32_bf16 v[34:37], v[154:157], v[170:173], v[34:37]
	v_mfma_f32_16x16x32_bf16 v[22:25], v[146:149], v[184:187], v[22:25]
	v_mfma_f32_16x16x32_bf16 v[18:21], v[154:157], v[184:187], v[18:21]
	v_mfma_f32_16x16x32_bf16 v[6:9], v[146:149], v[192:195], v[6:9]
	v_mfma_f32_16x16x32_bf16 v[2:5], v[154:157], v[192:195], v[2:5]
	v_mfma_f32_16x16x32_bf16 v[50:53], v[146:149], v[162:165], v[70:73]
	v_mfma_f32_16x16x32_bf16 v[54:57], v[154:157], v[162:165], v[66:69]
	v_mfma_f32_16x16x32_bf16 v[38:41], v[150:153], v[180:183], v[38:41]
	v_mfma_f32_16x16x32_bf16 v[34:37], v[158:161], v[180:183], v[34:37]
	v_mfma_f32_16x16x32_bf16 v[22:25], v[150:153], v[188:191], v[22:25]
	v_mfma_f32_16x16x32_bf16 v[18:21], v[158:161], v[188:191], v[18:21]
	v_mfma_f32_16x16x32_bf16 v[6:9], v[150:153], v[196:199], v[6:9]
	v_mfma_f32_16x16x32_bf16 v[2:5], v[158:161], v[196:199], v[2:5]
	v_mfma_f32_16x16x32_bf16 v[50:53], v[150:153], v[166:169], v[50:53]
	v_mfma_f32_16x16x32_bf16 v[54:57], v[158:161], v[166:169], v[54:57]
	s_barrier
	s_setprio 0
	s_add_i32 s34, 0, 0x18000
	s_add_i32 s35, 0, 0x1c000
	v_add_u32_e32 v70, s34, v209
	v_add_u32_e32 v158, s35, v209
	ds_read_b128 v[58:61], v70
	ds_read_b128 v[62:65], v70 offset:1024
	ds_read_b128 v[66:69], v70 offset:2048
	ds_read_b128 v[70:73], v70 offset:3072
	ds_read_b128 v[146:149], v158
	ds_read_b128 v[150:153], v158 offset:1024
	ds_read_b128 v[154:157], v158 offset:2048
	ds_read_b128 v[158:161], v158 offset:3072
	s_add_u32 s30, s58, 0x158000
	s_addc_u32 s31, s59, 0
	s_mov_b32 m0, s25
	v_lshl_add_u64 v[210:211], s[30:31], 0, v[0:1]
	ds_read_b128 v[162:165], v215 offset:32768
	ds_read_b128 v[166:169], v215 offset:33792
	ds_read_b128 v[170:173], v215 offset:34816
	ds_read_b128 v[180:183], v215 offset:35840
	ds_read_b128 v[184:187], v215 offset:36864
	ds_read_b128 v[188:191], v215 offset:37888
	ds_read_b128 v[192:195], v215 offset:38912
	ds_read_b128 v[196:199], v215 offset:39936
	global_load_lds_dwordx4 v[210:211], off
	v_lshl_add_u64 v[210:211], s[30:31], 0, v[174:175]
	s_mov_b32 m0, s66
	s_nop 0
	global_load_lds_dwordx4 v[210:211], off
	s_waitcnt vmcnt(8)
	s_waitcnt lgkmcnt(0)
	s_setprio 1
	s_barrier
	v_mfma_f32_16x16x32_bf16 v[142:145], v[58:61], v[162:165], v[142:145]
	v_mfma_f32_16x16x32_bf16 v[138:141], v[66:69], v[162:165], v[138:141]
	v_mfma_f32_16x16x32_bf16 v[126:129], v[58:61], v[170:173], v[126:129]
	v_mfma_f32_16x16x32_bf16 v[122:125], v[66:69], v[170:173], v[122:125]
	v_mfma_f32_16x16x32_bf16 v[110:113], v[58:61], v[184:187], v[110:113]
	v_mfma_f32_16x16x32_bf16 v[106:109], v[66:69], v[184:187], v[106:109]
	v_mfma_f32_16x16x32_bf16 v[94:97], v[58:61], v[192:195], v[94:97]
	v_mfma_f32_16x16x32_bf16 v[90:93], v[66:69], v[192:195], v[90:93]
	v_mfma_f32_16x16x32_bf16 v[142:145], v[62:65], v[166:169], v[142:145]
	v_mfma_f32_16x16x32_bf16 v[138:141], v[70:73], v[166:169], v[138:141]
	v_mfma_f32_16x16x32_bf16 v[126:129], v[62:65], v[180:183], v[126:129]
	v_mfma_f32_16x16x32_bf16 v[122:125], v[70:73], v[180:183], v[122:125]
	v_mfma_f32_16x16x32_bf16 v[110:113], v[62:65], v[188:191], v[110:113]
	v_mfma_f32_16x16x32_bf16 v[106:109], v[70:73], v[188:191], v[106:109]
	v_mfma_f32_16x16x32_bf16 v[94:97], v[62:65], v[196:199], v[94:97]
	v_mfma_f32_16x16x32_bf16 v[90:93], v[70:73], v[196:199], v[90:93]
	v_mfma_f32_16x16x32_bf16 v[134:137], v[146:149], v[162:165], v[134:137]
	v_mfma_f32_16x16x32_bf16 v[130:133], v[154:157], v[162:165], v[130:133]
	v_mfma_f32_16x16x32_bf16 v[118:121], v[146:149], v[170:173], v[118:121]
	v_mfma_f32_16x16x32_bf16 v[114:117], v[154:157], v[170:173], v[114:117]
	v_mfma_f32_16x16x32_bf16 v[102:105], v[146:149], v[184:187], v[102:105]
	v_mfma_f32_16x16x32_bf16 v[98:101], v[154:157], v[184:187], v[98:101]
	v_mfma_f32_16x16x32_bf16 v[86:89], v[146:149], v[192:195], v[86:89]
	v_mfma_f32_16x16x32_bf16 v[82:85], v[154:157], v[192:195], v[82:85]
	v_mfma_f32_16x16x32_bf16 v[134:137], v[150:153], v[166:169], v[134:137]
	v_mfma_f32_16x16x32_bf16 v[130:133], v[158:161], v[166:169], v[130:133]
	v_mfma_f32_16x16x32_bf16 v[118:121], v[150:153], v[180:183], v[118:121]
	v_mfma_f32_16x16x32_bf16 v[114:117], v[158:161], v[180:183], v[114:117]
	v_mfma_f32_16x16x32_bf16 v[102:105], v[150:153], v[188:191], v[102:105]
	v_mfma_f32_16x16x32_bf16 v[98:101], v[158:161], v[188:191], v[98:101]
	v_mfma_f32_16x16x32_bf16 v[86:89], v[150:153], v[196:199], v[86:89]
	v_mfma_f32_16x16x32_bf16 v[82:85], v[158:161], v[196:199], v[82:85]
	s_barrier
; #define PG8_STAGE(bufoff, gbase, voff) do { _Pragma("unroll") for (int _i = 0; _i < 2; ++_i) \
;         __builtin_amdgcn_global_load_lds((const unsigned*)((const char*)(gbase) + (voff)[_i]), (LAS unsigned*)(lds + (bufoff) + ldsw + _i * 8192), 16, 0, 0); } while (0)
; #define PG8_LDA(dst, b, h) do { _Pragma("unroll") for (int m = 0; m < 4; ++m) _Pragma("unroll") for (int k = 0; k < 2; ++k) dst[m][k] = *(const LAS bf16x8*)(lds + PG8_SA(b, h) + aoff + m * 2048 + k * 1024); } while (0)
; #define PG8_MMA(ai, bj, At, Bt) do { __builtin_amdgcn_s_setprio(1); _Pragma("unroll") for (int m = 0; m < 4; ++m) _Pragma("unroll") for (int n = 0; n < 2; ++n) _Pragma("unroll") for (int k = 0; k < 2; ++k) \
;         acc[ai][bj][m][n] = __builtin_amdgcn_mfma_f32_16x16x32_bf16(Bt[n][k], At[m][k], acc[ai][bj][m][n], 0, 0, 0); __builtin_amdgcn_s_setprio(0); } while (0)
; #define PG8_WAIT_V(n) asm volatile("s_waitcnt vmcnt(" #n ")" ::: "memory")
; #define PG8_WAIT_L(n) asm volatile("s_waitcnt lgkmcnt(" #n ")" ::: "memory")
; #define PG8_BAR __builtin_amdgcn_s_barrier()
; #define PG8_SCHED __builtin_amdgcn_sched_barrier(0)
; template <class Epi, int AMODE>
; __device__ __forceinline__ void gemm_phase(LAS unsigned char* lds, const Gemm g, const StaticOrder& S, const Epi& E, int stagger_us, int tid_in) {
;     ...
;             PG8_LDA(At, 1, 1); PG8_STAGE(PG8_SB(1, 0), b3, voffB); PG8_STAGE(PG8_SB(1, 1), b3 + hstepB, voffB); PG8_STAGE(PG8_SA(1, 0), a3, voffA);
;             PG8_WAIT_V(8); PG8_WAIT_L(0); PG8_BAR; PG8_MMA(1, 0, At, B0); PG8_MMA(1, 1, At, B1); PG8_BAR; PG8_SCHED;
	s_setprio 0
	s_add_i32 s30, s34, s12
	v_lshl_add_u64 v[200:201], v[200:201], 0, s[74:75]
	s_mov_b32 m0, s30
	ds_read_b128 v[162:165], v215 offset:49152
	ds_read_b128 v[166:169], v215 offset:50176
	ds_read_b128 v[170:173], v215 offset:51200
	ds_read_b128 v[180:183], v215 offset:52224
	ds_read_b128 v[184:187], v215 offset:53248
	ds_read_b128 v[188:191], v215 offset:54272
	ds_read_b128 v[192:195], v215 offset:55296
	ds_read_b128 v[196:199], v215 offset:56320
	global_load_lds_dwordx4 v[200:201], off
	s_add_i32 m0, s30, 0x2000
	s_add_u32 s6, s6, 0x158080
	v_lshl_add_u64 v[200:201], v[202:203], 0, s[74:75]
	s_addc_u32 s7, s7, 0
	s_add_i32 s30, s35, s12
	global_load_lds_dwordx4 v[200:201], off
	v_lshl_add_u64 v[200:201], s[6:7], 0, v[0:1]
	s_mov_b32 m0, s30
	s_nop 0
	global_load_lds_dwordx4 v[200:201], off
	v_lshl_add_u64 v[200:201], s[6:7], 0, v[174:175]
	s_add_i32 m0, s30, 0x2000
	s_nop 0
	global_load_lds_dwordx4 v[200:201], off
	v_lshl_add_u64 v[200:201], v[204:205], 0, s[74:75]
	s_mov_b32 m0, s79
	s_nop 0
	global_load_lds_dwordx4 v[200:201], off
	v_lshl_add_u64 v[200:201], v[206:207], 0, s[74:75]
	s_mov_b32 m0, s83
	s_nop 0
	global_load_lds_dwordx4 v[200:201], off
	s_waitcnt vmcnt(8)
	s_waitcnt lgkmcnt(0)
	s_setprio 1
	s_barrier
	v_mfma_f32_16x16x32_bf16 v[78:81], v[58:61], v[162:165], v[78:81]
	v_mfma_f32_16x16x32_bf16 v[74:77], v[66:69], v[162:165], v[74:77]
	v_mfma_f32_16x16x32_bf16 v[46:49], v[58:61], v[170:173], v[46:49]
	v_mfma_f32_16x16x32_bf16 v[42:45], v[66:69], v[170:173], v[42:45]
	v_mfma_f32_16x16x32_bf16 v[30:33], v[58:61], v[184:187], v[30:33]
	v_mfma_f32_16x16x32_bf16 v[26:29], v[66:69], v[184:187], v[26:29]
	v_mfma_f32_16x16x32_bf16 v[14:17], v[58:61], v[192:195], v[14:17]
	v_mfma_f32_16x16x32_bf16 v[10:13], v[66:69], v[192:195], v[10:13]
	v_mfma_f32_16x16x32_bf16 v[78:81], v[62:65], v[166:169], v[78:81]
	v_mfma_f32_16x16x32_bf16 v[74:77], v[70:73], v[166:169], v[74:77]
	v_mfma_f32_16x16x32_bf16 v[46:49], v[62:65], v[180:183], v[46:49]
	v_mfma_f32_16x16x32_bf16 v[42:45], v[70:73], v[180:183], v[42:45]
	v_mfma_f32_16x16x32_bf16 v[30:33], v[62:65], v[188:191], v[30:33]
	v_mfma_f32_16x16x32_bf16 v[26:29], v[70:73], v[188:191], v[26:29]
	v_mfma_f32_16x16x32_bf16 v[14:17], v[62:65], v[196:199], v[14:17]
	v_mfma_f32_16x16x32_bf16 v[10:13], v[70:73], v[196:199], v[10:13]
	v_mfma_f32_16x16x32_bf16 v[50:53], v[146:149], v[162:165], v[50:53]
	v_mfma_f32_16x16x32_bf16 v[70:73], v[150:153], v[166:169], v[50:53]
	v_mfma_f32_16x16x32_bf16 v[50:53], v[154:157], v[162:165], v[54:57]
	v_mfma_f32_16x16x32_bf16 v[38:41], v[146:149], v[170:173], v[38:41]
	v_mfma_f32_16x16x32_bf16 v[34:37], v[154:157], v[170:173], v[34:37]
	v_mfma_f32_16x16x32_bf16 v[22:25], v[146:149], v[184:187], v[22:25]
	v_mfma_f32_16x16x32_bf16 v[18:21], v[154:157], v[184:187], v[18:21]
	v_mfma_f32_16x16x32_bf16 v[6:9], v[146:149], v[192:195], v[6:9]
	v_mfma_f32_16x16x32_bf16 v[2:5], v[154:157], v[192:195], v[2:5]
	v_mfma_f32_16x16x32_bf16 v[66:69], v[158:161], v[166:169], v[50:53]
	v_mfma_f32_16x16x32_bf16 v[38:41], v[150:153], v[180:183], v[38:41]
	v_mfma_f32_16x16x32_bf16 v[34:37], v[158:161], v[180:183], v[34:37]
	v_mfma_f32_16x16x32_bf16 v[22:25], v[150:153], v[188:191], v[22:25]
	v_mfma_f32_16x16x32_bf16 v[18:21], v[158:161], v[188:191], v[18:21]
	v_mfma_f32_16x16x32_bf16 v[6:9], v[150:153], v[196:199], v[6:9]
	v_mfma_f32_16x16x32_bf16 v[2:5], v[158:161], v[196:199], v[2:5]
	s_barrier
	s_setprio 0
	s_add_i32 s29, s29, 2
	s_add_u32 s27, s27, 0x100
	s_addc_u32 s28, s28, 0
	s_cmpk_gt_u32 s29, 0x53
	s_mov_b64 s[46:47], s[4:5]
	s_cbranch_scc0 .LBB0_1498
	s_and_b64 vcc, exec, s[54:55]
	s_cbranch_vccz .LBB0_1501
	s_barrier
